# GU: MFMAs of the last k-step's block 3 / next tile's block 2 re-ordered by row group so each epilogue half spreads over two MFMA blocks
# baseline (speedup 1.0000x reference)
; __device__ __forceinline__ unsigned cvt_pk_bf16(float lo, float hi) { unsigned r; asm volatile("v_cvt_pk_bf16_f32 %0, %1, %2" : "=v"(r) : "v"(lo), "v"(hi)); return r; }
; __device__ __forceinline__ float siluf_(float x) { return x * sigmoidf_(x); }
; #define PG8_STAGE(bufoff, gbase, voff) do { _Pragma("unroll") for (int _i = 0; _i < 2; ++_i) \
;         __builtin_amdgcn_global_load_lds((const unsigned*)((const char*)(gbase) + (voff)[_i]), (LAS unsigned*)(lds + (bufoff) + ldsw + _i * 8192), 16, 0, 0); } while (0)
; #define PG8_LDA(dst, b, h) do { _Pragma("unroll") for (int m = 0; m < 4; ++m) _Pragma("unroll") for (int k = 0; k < 2; ++k) dst[m][k] = *(const LAS bf16x8*)(lds + PG8_SA(b, h) + aoff + m * 2048 + k * 1024); } while (0)
; #define PG8_LDB(dst, b, h) do { _Pragma("unroll") for (int n = 0; n < 2; ++n) _Pragma("unroll") for (int k = 0; k < 2; ++k) dst[n][k] = *(const LAS bf16x8*)(lds + PG8_SB(b, h) + boff + n * 2048 + k * 1024); } while (0)
; #define PG8_WAIT_V(n) asm volatile("s_waitcnt vmcnt(" #n ")" ::: "memory")
; #define PG8_WAIT_L(n) asm volatile("s_waitcnt lgkmcnt(" #n ")" ::: "memory")
; #define PG8_BAR __builtin_amdgcn_s_barrier()
; #define PG8_SCHED __builtin_amdgcn_sched_barrier(0)
;     __device__ __forceinline__ void operator()(const f32x4 (&acc)[2][2][4][2], const Unit& u, int wr, int wc, int fr, int fq) const {
;     ...
;             for (int m = 0; m < 4; ++m) { const int row = row0 + ai * HALF + m * 16; bf16_t* rowp = O + (size_t)row * ldc + col0; const float rs = rsv[ai][m];
;                 f32x4 v0, v1;
; #pragma unroll
;                 for (int j = 0; j < 4; ++j) { v0[j] = siluf_(acc[ai][0][m][0][j] * rs) * (acc[ai][1][m][0][j] * rs); v1[j] = siluf_(acc[ai][0][m][1][j] * rs) * (acc[ai][1][m][1][j] * rs); }
;                 u32x4 w; w.x = cvt_pk_bf16(v0[0], v0[1]); w.y = cvt_pk_bf16(v0[2], v0[3]); w.z = cvt_pk_bf16(v1[0], v1[1]); w.w = cvt_pk_bf16(v1[2], v1[3]);
;                 *(u32x4*)rowp = w; }
; template <class Epi, bool ALIGN_EPI>
; __device__ __forceinline__ void gemm_phase(LAS unsigned char* lds, const Gemm g, const StaticOrder& S, const Epi& E, const int tid) {
;     ...
;             PG8_LDB(B0, 0, 0); PG8_LDB(B1, 0, 1); PG8_SCHED; PG8_LDA(At, 0, 0); PG8_STAGE(PG8_SA(1, 1), a1 + hA, voffA);
;             PG8_WAIT_V(8); PG8_WAIT_L(0); PG8_BAR; PG8_MMA(0, 0, At, B0); PG8_MMA(0, 1, At, B1); PG8_BAR; PG8_SCHED;
.Lgu_first_epi:
	s_add_i32 s11, s10, 2
	s_cmp_eq_u32 s58, s10
	v_lshl_add_u64 v[146:147], v[142:143], 0, s[92:93]
	s_cselect_b64 vcc, -1, 0
	v_add_u32_e32 v150, s33, v151
	s_add_i32 s10, 0, 0x14000
	v_cndmask_b32_e32 v167, v147, v139, vcc
	v_cndmask_b32_e32 v166, v146, v138, vcc
	ds_read_b128 v[146:149], v150
	ds_read_b128 v[154:157], v150 offset:1024
	ds_read_b128 v[158:161], v150 offset:2048
	ds_read_b128 v[162:165], v150 offset:3072
	v_add_u32_e32 v150, s10, v151
	ds_read_b128 v[176:179], v150
	ds_read_b128 v[180:183], v150 offset:1024
	ds_read_b128 v[184:187], v150 offset:2048
	ds_read_b128 v[188:191], v150 offset:3072
	v_cndmask_b32_e32 v221, v145, v141, vcc
	v_cndmask_b32_e32 v220, v144, v140, vcc
	v_lshl_add_u64 v[226:227], v[142:143], 0, v[134:135]
	s_add_i32 m0, s51, 0xc000
	ds_read_b128 v[192:195], v153
	ds_read_b128 v[196:199], v153 offset:1024
	ds_read_b128 v[200:203], v153 offset:2048
	ds_read_b128 v[204:207], v153 offset:3072
	ds_read_b128 v[208:211], v153 offset:4096
	ds_read_b128 v[212:215], v153 offset:5120
	ds_read_b128 v[216:219], v153 offset:6144
	ds_read_b128 v[240:243], v153 offset:7168
	global_load_lds_dwordx4 v[226:227], off
	v_lshl_add_u64 v[226:227], v[142:143], 0, v[136:137]
	s_add_i32 m0, s51, 0xe000
	s_nop 0
	global_load_lds_dwordx4 v[226:227], off
	s_waitcnt vmcnt(12)
	s_waitcnt lgkmcnt(0)
	s_barrier
	s_setprio 1
	s_waitcnt lgkmcnt(0)
	v_mfma_f32_16x16x32_bf16 v[120:123], v[146:149], v[192:195], 0
	s_lshl_b32 s98, s28, 5
	s_mov_b32 s99, 0
	s_mov_b32 s100, 0xbfb8aa3b
	s_mov_b32 s101, 0xbfb8aa3b
	v_mul_f32_e32 v56, v238, v56
	v_mul_f32_e32 v57, v238, v57
	v_mfma_f32_16x16x32_bf16 v[112:115], v[158:161], v[192:195], 0
	v_mul_f32_e32 v58, v238, v58
	v_mul_f32_e32 v59, v238, v59
	v_mul_f32_e32 v60, v238, v60
	v_mul_f32_e32 v61, v238, v61
	v_mul_f32_e32 v62, v238, v62
	v_mul_f32_e32 v63, v238, v63
	v_mfma_f32_16x16x32_bf16 v[104:107], v[146:149], v[200:203], 0
	v_mul_f32_e32 v224, s100, v56
	v_mul_f32_e32 v225, s101, v57
	v_mul_f32_e32 v228, s100, v58
	v_mul_f32_e32 v229, s101, v59
	v_exp_f32_e32 v224, v224
	v_exp_f32_e32 v225, v225
	v_mfma_f32_16x16x32_bf16 v[96:99], v[158:161], v[200:203], 0
	v_exp_f32_e32 v228, v228
	v_exp_f32_e32 v229, v229
	v_add_f32_e32 v224, 1.0, v224
	v_add_f32_e32 v225, 1.0, v225
	v_add_f32_e32 v228, 1.0, v228
	v_add_f32_e32 v229, 1.0, v229
	v_mfma_f32_16x16x32_bf16 v[88:91], v[146:149], v[208:211], 0
	v_rcp_f32_e32 v224, v224
	v_rcp_f32_e32 v225, v225
	v_rcp_f32_e32 v228, v228
	v_rcp_f32_e32 v229, v229
	v_nop
	v_mul_f32_e32 v56, v224, v56
	v_mfma_f32_16x16x32_bf16 v[80:83], v[158:161], v[208:211], 0
	v_mul_f32_e32 v57, v225, v57
	v_mul_f32_e32 v58, v228, v58
	v_mul_f32_e32 v59, v229, v59
	v_mul_f32_e32 v56, v60, v56
	v_mul_f32_e32 v57, v61, v57
	v_mul_f32_e32 v58, v62, v58
	v_mfma_f32_16x16x32_bf16 v[72:75], v[146:149], v[216:219], 0
	v_mul_f32_e32 v59, v63, v59
	v_mul_f32_e32 v48, v238, v48
	v_mul_f32_e32 v49, v238, v49
	v_mul_f32_e32 v50, v238, v50
	v_mul_f32_e32 v51, v238, v51
	v_mul_f32_e32 v52, v238, v52
	v_mfma_f32_16x16x32_bf16 v[64:67], v[158:161], v[216:219], 0
	v_mul_f32_e32 v53, v238, v53
	v_mul_f32_e32 v54, v238, v54
	v_mul_f32_e32 v55, v238, v55
	v_mul_f32_e32 v224, s100, v48
	v_mul_f32_e32 v225, s101, v49
	v_mul_f32_e32 v228, s100, v50
	v_mfma_f32_16x16x32_bf16 v[120:123], v[154:157], v[196:199], v[120:123]
	v_mul_f32_e32 v229, s101, v51
	v_exp_f32_e32 v224, v224
	v_exp_f32_e32 v225, v225
	v_exp_f32_e32 v228, v228
	v_exp_f32_e32 v229, v229
	v_add_f32_e32 v224, 1.0, v224
	v_mfma_f32_16x16x32_bf16 v[112:115], v[162:165], v[196:199], v[112:115]
	v_add_f32_e32 v225, 1.0, v225
	v_add_f32_e32 v228, 1.0, v228
	v_add_f32_e32 v229, 1.0, v229
	v_rcp_f32_e32 v224, v224
	v_rcp_f32_e32 v225, v225
	v_rcp_f32_e32 v228, v228
	v_mfma_f32_16x16x32_bf16 v[104:107], v[154:157], v[204:207], v[104:107]
	v_rcp_f32_e32 v229, v229
	v_nop
	v_mul_f32_e32 v48, v224, v48
	v_mul_f32_e32 v49, v225, v49
	v_mul_f32_e32 v50, v228, v50
	v_mul_f32_e32 v51, v229, v51
	v_mfma_f32_16x16x32_bf16 v[96:99], v[162:165], v[204:207], v[96:99]
	v_mul_f32_e32 v48, v52, v48
	v_mul_f32_e32 v49, v53, v49
	v_mul_f32_e32 v50, v54, v50
	v_mul_f32_e32 v51, v55, v51
	v_cvt_pk_bf16_f32 v56, v56, v57
	v_cvt_pk_bf16_f32 v57, v58, v59
	v_mfma_f32_16x16x32_bf16 v[88:91], v[154:157], v[212:215], v[88:91]
	v_cvt_pk_bf16_f32 v58, v48, v49
	v_cvt_pk_bf16_f32 v59, v50, v51
	global_store_dwordx4 v[232:233], v[56:59], off
	v_lshl_add_u64 v[232:233], v[232:233], 0, s[98:99]
	v_mul_f32_e32 v40, v239, v40
	v_mul_f32_e32 v41, v239, v41
	v_mfma_f32_16x16x32_bf16 v[80:83], v[162:165], v[212:215], v[80:83]
	v_mul_f32_e32 v42, v239, v42
	v_mul_f32_e32 v43, v239, v43
	v_mul_f32_e32 v44, v239, v44
	v_mul_f32_e32 v45, v239, v45
	v_mul_f32_e32 v46, v239, v46
	v_mul_f32_e32 v47, v239, v47
	v_mfma_f32_16x16x32_bf16 v[72:75], v[154:157], v[240:243], v[72:75]
	v_mul_f32_e32 v224, s100, v40
	v_mul_f32_e32 v225, s101, v41
	v_mul_f32_e32 v228, s100, v42
	v_mul_f32_e32 v229, s101, v43
	v_exp_f32_e32 v224, v224
	v_exp_f32_e32 v225, v225
	v_mfma_f32_16x16x32_bf16 v[64:67], v[162:165], v[240:243], v[64:67]
	v_exp_f32_e32 v228, v228
	v_exp_f32_e32 v229, v229
	v_add_f32_e32 v224, 1.0, v224
	v_add_f32_e32 v225, 1.0, v225
	v_add_f32_e32 v228, 1.0, v228
	v_add_f32_e32 v229, 1.0, v229
	s_setprio 0
	s_setprio 1
	v_mfma_f32_16x16x32_bf16 v[124:127], v[176:179], v[192:195], 0
	v_rcp_f32_e32 v224, v224
	v_rcp_f32_e32 v225, v225
	v_rcp_f32_e32 v228, v228
	v_rcp_f32_e32 v229, v229
	v_nop
	v_mul_f32_e32 v40, v224, v40
	v_mfma_f32_16x16x32_bf16 v[116:119], v[184:187], v[192:195], 0
	v_mul_f32_e32 v41, v225, v41
	v_mul_f32_e32 v42, v228, v42
	v_mul_f32_e32 v43, v229, v43
; __device__ __forceinline__ unsigned cvt_pk_bf16(float lo, float hi) { unsigned r; asm volatile("v_cvt_pk_bf16_f32 %0, %1, %2" : "=v"(r) : "v"(lo), "v"(hi)); return r; }
; __device__ __forceinline__ float siluf_(float x) { return x * sigmoidf_(x); }
; #define PG8_STAGE(bufoff, gbase, voff) do { _Pragma("unroll") for (int _i = 0; _i < 2; ++_i) \
;         __builtin_amdgcn_global_load_lds((const unsigned*)((const char*)(gbase) + (voff)[_i]), (LAS unsigned*)(lds + (bufoff) + ldsw + _i * 8192), 16, 0, 0); } while (0)
; #define PG8_LDA(dst, b, h) do { _Pragma("unroll") for (int m = 0; m < 4; ++m) _Pragma("unroll") for (int k = 0; k < 2; ++k) dst[m][k] = *(const LAS bf16x8*)(lds + PG8_SA(b, h) + aoff + m * 2048 + k * 1024); } while (0)
; #define PG8_MMA(ai, bj, At, Bt) do { __builtin_amdgcn_s_setprio(1); _Pragma("unroll") for (int k = 0; k < 2; ++k) _Pragma("unroll") for (int m = 0; m < 4; ++m) _Pragma("unroll") for (int n = 0; n < 2; ++n) \
;         acc[ai][bj][m][n] = __builtin_amdgcn_mfma_f32_16x16x32_bf16(Bt[n][k], At[m][k], acc[ai][bj][m][n], 0, 0, 0); __builtin_amdgcn_s_setprio(0); } while (0)
; #define PG8_WAIT_V(n) asm volatile("s_waitcnt vmcnt(" #n ")" ::: "memory")
;     __device__ __forceinline__ void operator()(const f32x4 (&acc)[2][2][4][2], const Unit& u, int wr, int wc, int fr, int fq) const {
;     ...
;             for (int m = 0; m < 4; ++m) { const int row = row0 + ai * HALF + m * 16; bf16_t* rowp = O + (size_t)row * ldc + col0; const float rs = rsv[ai][m];
;                 f32x4 v0, v1;
; #pragma unroll
;                 for (int j = 0; j < 4; ++j) { v0[j] = siluf_(acc[ai][0][m][0][j] * rs) * (acc[ai][1][m][0][j] * rs); v1[j] = siluf_(acc[ai][0][m][1][j] * rs) * (acc[ai][1][m][1][j] * rs); }
;                 u32x4 w; w.x = cvt_pk_bf16(v0[0], v0[1]); w.y = cvt_pk_bf16(v0[2], v0[3]); w.z = cvt_pk_bf16(v1[0], v1[1]); w.w = cvt_pk_bf16(v1[2], v1[3]);
;                 *(u32x4*)rowp = w; }
; template <class Epi, bool ALIGN_EPI>
; __device__ __forceinline__ void gemm_phase(LAS unsigned char* lds, const Gemm g, const StaticOrder& S, const Epi& E, const int tid) {
;     ...
;             PG8_WAIT_V(8); PG8_WAIT_L(0); PG8_BAR; PG8_MMA(0, 0, At, B0); PG8_MMA(0, 1, At, B1); PG8_BAR; PG8_SCHED;
;             PG8_LDA(At, 0, 1); PG8_STAGE(PG8_SB(0, 0), b2, voffB); PG8_STAGE(PG8_SB(0, 1), b2 + hB, voffB); PG8_STAGE(PG8_SA(0, 0), a2, voffA);
	v_mul_f32_e32 v40, v44, v40
	v_mul_f32_e32 v41, v45, v41
	v_mul_f32_e32 v42, v46, v42
	v_mfma_f32_16x16x32_bf16 v[108:111], v[176:179], v[200:203], 0
	v_mul_f32_e32 v43, v47, v43
	v_mul_f32_e32 v32, v239, v32
	v_mul_f32_e32 v33, v239, v33
	v_mul_f32_e32 v34, v239, v34
	v_mul_f32_e32 v35, v239, v35
	v_mul_f32_e32 v36, v239, v36
	v_mfma_f32_16x16x32_bf16 v[100:103], v[184:187], v[200:203], 0
	v_mul_f32_e32 v37, v239, v37
	v_mul_f32_e32 v38, v239, v38
	v_mul_f32_e32 v39, v239, v39
	v_mul_f32_e32 v224, s100, v32
	v_mul_f32_e32 v225, s101, v33
	v_mul_f32_e32 v228, s100, v34
	v_mfma_f32_16x16x32_bf16 v[92:95], v[176:179], v[208:211], 0
	v_mul_f32_e32 v229, s101, v35
	v_exp_f32_e32 v224, v224
	v_exp_f32_e32 v225, v225
	v_exp_f32_e32 v228, v228
	v_exp_f32_e32 v229, v229
	v_add_f32_e32 v224, 1.0, v224
	v_mfma_f32_16x16x32_bf16 v[84:87], v[184:187], v[208:211], 0
	v_add_f32_e32 v225, 1.0, v225
	v_add_f32_e32 v228, 1.0, v228
	v_add_f32_e32 v229, 1.0, v229
	v_rcp_f32_e32 v224, v224
	v_rcp_f32_e32 v225, v225
	v_rcp_f32_e32 v228, v228
	v_mfma_f32_16x16x32_bf16 v[76:79], v[176:179], v[216:219], 0
	v_rcp_f32_e32 v229, v229
	v_nop
	v_mul_f32_e32 v32, v224, v32
	v_mul_f32_e32 v33, v225, v33
	v_mul_f32_e32 v34, v228, v34
	v_mul_f32_e32 v35, v229, v35
	v_mfma_f32_16x16x32_bf16 v[68:71], v[184:187], v[216:219], 0
	v_mul_f32_e32 v32, v36, v32
	v_mul_f32_e32 v33, v37, v33
	v_mul_f32_e32 v34, v38, v34
	v_mul_f32_e32 v35, v39, v35
	v_cvt_pk_bf16_f32 v40, v40, v41
	v_cvt_pk_bf16_f32 v41, v42, v43
	v_mfma_f32_16x16x32_bf16 v[124:127], v[180:183], v[196:199], v[124:127]
	v_cvt_pk_bf16_f32 v42, v32, v33
	v_cvt_pk_bf16_f32 v43, v34, v35
	global_store_dwordx4 v[232:233], v[40:43], off
	v_lshl_add_u64 v[232:233], v[232:233], 0, s[98:99]
	v_mul_f32_e32 v24, v230, v24
	v_mul_f32_e32 v25, v230, v25
	v_mfma_f32_16x16x32_bf16 v[116:119], v[188:191], v[196:199], v[116:119]
	v_mul_f32_e32 v26, v230, v26
	v_mul_f32_e32 v27, v230, v27
	v_mul_f32_e32 v28, v230, v28
	v_mul_f32_e32 v29, v230, v29
	v_mul_f32_e32 v30, v230, v30
	v_mul_f32_e32 v31, v230, v31
	v_mfma_f32_16x16x32_bf16 v[108:111], v[180:183], v[204:207], v[108:111]
	v_mul_f32_e32 v224, s100, v24
	v_mul_f32_e32 v225, s101, v25
	v_mul_f32_e32 v228, s100, v26
	v_mul_f32_e32 v229, s101, v27
	v_exp_f32_e32 v224, v224
	v_exp_f32_e32 v225, v225
	v_mfma_f32_16x16x32_bf16 v[100:103], v[188:191], v[204:207], v[100:103]
	v_exp_f32_e32 v228, v228
	v_exp_f32_e32 v229, v229
	v_add_f32_e32 v224, 1.0, v224
	v_add_f32_e32 v225, 1.0, v225
	v_add_f32_e32 v228, 1.0, v228
	v_add_f32_e32 v229, 1.0, v229
	v_mfma_f32_16x16x32_bf16 v[92:95], v[180:183], v[212:215], v[92:95]
	v_rcp_f32_e32 v224, v224
	v_rcp_f32_e32 v225, v225
	v_rcp_f32_e32 v228, v228
	v_rcp_f32_e32 v229, v229
	v_nop
	v_mul_f32_e32 v24, v224, v24
	v_mfma_f32_16x16x32_bf16 v[84:87], v[188:191], v[212:215], v[84:87]
	v_mul_f32_e32 v25, v225, v25
	v_mul_f32_e32 v26, v228, v26
	v_mul_f32_e32 v27, v229, v27
	v_mul_f32_e32 v24, v28, v24
	v_mul_f32_e32 v25, v29, v25
	v_mul_f32_e32 v26, v30, v26
	v_mfma_f32_16x16x32_bf16 v[76:79], v[180:183], v[240:243], v[76:79]
	v_mul_f32_e32 v27, v31, v27
	v_mul_f32_e32 v16, v230, v16
	v_mul_f32_e32 v17, v230, v17
	v_mul_f32_e32 v18, v230, v18
	v_mul_f32_e32 v19, v230, v19
	v_mul_f32_e32 v20, v230, v20
	v_mfma_f32_16x16x32_bf16 v[68:71], v[188:191], v[240:243], v[68:71]
	v_mul_f32_e32 v21, v230, v21
	v_mul_f32_e32 v22, v230, v22
	v_mul_f32_e32 v23, v230, v23
	v_mul_f32_e32 v224, s100, v16
	v_mul_f32_e32 v225, s101, v17
	v_mul_f32_e32 v228, s100, v18
	s_setprio 0
	s_barrier
	s_add_i32 s65, s33, s45
	v_lshl_add_u64 v[226:227], v[220:221], 0, v[168:169]
	s_mov_b32 m0, s65
	ds_read_b128 v[192:195], v153 offset:16384
	ds_read_b128 v[196:199], v153 offset:17408
	ds_read_b128 v[200:203], v153 offset:18432
	ds_read_b128 v[204:207], v153 offset:19456
	ds_read_b128 v[208:211], v153 offset:20480
	ds_read_b128 v[212:215], v153 offset:21504
	ds_read_b128 v[216:219], v153 offset:22528
	ds_read_b128 v[240:243], v153 offset:23552
	global_load_lds_dwordx4 v[226:227], off
	v_lshl_add_u64 v[244:245], v[220:221], 0, v[128:129]
	s_add_i32 m0, s65, 0x2000
	v_lshl_add_u64 v[220:221], v[220:221], 0, s[12:13]
	s_add_i32 s10, s10, s45
	global_load_lds_dwordx4 v[244:245], off
	v_lshl_add_u64 v[246:247], v[220:221], 0, v[168:169]
	s_mov_b32 m0, s10
	v_lshl_add_u64 v[220:221], v[220:221], 0, v[128:129]
	global_load_lds_dwordx4 v[246:247], off
	s_add_i32 m0, s10, 0x2000
	v_lshl_add_u64 v[248:249], v[166:167], 0, v[132:133]
	global_load_lds_dwordx4 v[220:221], off
	s_mov_b32 m0, s51
	v_lshl_add_u64 v[250:251], v[166:167], 0, v[130:131]
	global_load_lds_dwordx4 v[248:249], off
	s_mov_b32 m0, s52
	s_nop 0
	global_load_lds_dwordx4 v[250:251], off
	s_waitcnt vmcnt(13)
	s_waitcnt lgkmcnt(0)
	s_barrier
; __device__ __forceinline__ unsigned cvt_pk_bf16(float lo, float hi) { unsigned r; asm volatile("v_cvt_pk_bf16_f32 %0, %1, %2" : "=v"(r) : "v"(lo), "v"(hi)); return r; }
; __device__ __forceinline__ float siluf_(float x) { return x * sigmoidf_(x); }
; #define PG8_STAGE(bufoff, gbase, voff) do { _Pragma("unroll") for (int _i = 0; _i < 2; ++_i) \
;         __builtin_amdgcn_global_load_lds((const unsigned*)((const char*)(gbase) + (voff)[_i]), (LAS unsigned*)(lds + (bufoff) + ldsw + _i * 8192), 16, 0, 0); } while (0)
; #define PG8_LDA(dst, b, h) do { _Pragma("unroll") for (int m = 0; m < 4; ++m) _Pragma("unroll") for (int k = 0; k < 2; ++k) dst[m][k] = *(const LAS bf16x8*)(lds + PG8_SA(b, h) + aoff + m * 2048 + k * 1024); } while (0)
; #define PG8_LDB(dst, b, h) do { _Pragma("unroll") for (int n = 0; n < 2; ++n) _Pragma("unroll") for (int k = 0; k < 2; ++k) dst[n][k] = *(const LAS bf16x8*)(lds + PG8_SB(b, h) + boff + n * 2048 + k * 1024); } while (0)
; #define PG8_WAIT_V(n) asm volatile("s_waitcnt vmcnt(" #n ")" ::: "memory")
; #define PG8_WAIT_L(n) asm volatile("s_waitcnt lgkmcnt(" #n ")" ::: "memory")
; #define PG8_BAR __builtin_amdgcn_s_barrier()
; #define PG8_SCHED __builtin_amdgcn_sched_barrier(0)
;     __device__ __forceinline__ void operator()(const f32x4 (&acc)[2][2][4][2], const Unit& u, int wr, int wc, int fr, int fq) const {
;     ...
;             for (int m = 0; m < 4; ++m) { const int row = row0 + ai * HALF + m * 16; bf16_t* rowp = O + (size_t)row * ldc + col0; const float rs = rsv[ai][m];
;                 f32x4 v0, v1;
; #pragma unroll
;                 for (int j = 0; j < 4; ++j) { v0[j] = siluf_(acc[ai][0][m][0][j] * rs) * (acc[ai][1][m][0][j] * rs); v1[j] = siluf_(acc[ai][0][m][1][j] * rs) * (acc[ai][1][m][1][j] * rs); }
;                 u32x4 w; w.x = cvt_pk_bf16(v0[0], v0[1]); w.y = cvt_pk_bf16(v0[2], v0[3]); w.z = cvt_pk_bf16(v1[0], v1[1]); w.w = cvt_pk_bf16(v1[2], v1[3]);
;                 *(u32x4*)rowp = w; }
; template <class Epi, bool ALIGN_EPI>
; __device__ __forceinline__ void gemm_phase(LAS unsigned char* lds, const Gemm g, const StaticOrder& S, const Epi& E, const int tid) {
;     ...
;             PG8_WAIT_V(8); PG8_WAIT_L(0); PG8_BAR; PG8_MMA(1, 0, At, B0); PG8_MMA(1, 1, At, B1); PG8_BAR; PG8_SCHED;
;             PG8_LDB(B0, 1, 0); PG8_LDB(B1, 1, 1); PG8_SCHED; PG8_LDA(At, 1, 0); PG8_STAGE(PG8_SA(0, 1), a2 + hA, voffA);
	s_setprio 1
	s_waitcnt lgkmcnt(0)
	v_mfma_f32_16x16x32_bf16 v[56:59], v[146:149], v[192:195], 0
	v_mul_f32_e32 v229, s101, v19
	v_exp_f32_e32 v224, v224
	v_exp_f32_e32 v225, v225
	v_exp_f32_e32 v228, v228
	v_exp_f32_e32 v229, v229
	v_add_f32_e32 v224, 1.0, v224
	v_mfma_f32_16x16x32_bf16 v[48:51], v[158:161], v[192:195], 0
	v_add_f32_e32 v225, 1.0, v225
	v_add_f32_e32 v228, 1.0, v228
	v_add_f32_e32 v229, 1.0, v229
	v_rcp_f32_e32 v224, v224
	v_rcp_f32_e32 v225, v225
	v_rcp_f32_e32 v228, v228
	v_mfma_f32_16x16x32_bf16 v[56:59], v[154:157], v[196:199], v[56:59]
	v_rcp_f32_e32 v229, v229
	v_nop
	v_mul_f32_e32 v16, v224, v16
	v_mul_f32_e32 v17, v225, v17
	v_mul_f32_e32 v18, v228, v18
	v_mul_f32_e32 v19, v229, v19
	v_mfma_f32_16x16x32_bf16 v[48:51], v[162:165], v[196:199], v[48:51]
	v_mul_f32_e32 v16, v20, v16
	v_mul_f32_e32 v17, v21, v17
	v_mul_f32_e32 v18, v22, v18
	v_mul_f32_e32 v19, v23, v19
	v_cvt_pk_bf16_f32 v24, v24, v25
	v_cvt_pk_bf16_f32 v25, v26, v27
	v_mfma_f32_16x16x32_bf16 v[60:63], v[176:179], v[192:195], 0
	v_cvt_pk_bf16_f32 v26, v16, v17
	v_cvt_pk_bf16_f32 v27, v18, v19
	global_store_dwordx4 v[232:233], v[24:27], off
	v_lshl_add_u64 v[232:233], v[232:233], 0, s[98:99]
	v_mul_f32_e32 v8, v231, v8
	v_mul_f32_e32 v9, v231, v9
	v_mfma_f32_16x16x32_bf16 v[52:55], v[184:187], v[192:195], 0
	v_mul_f32_e32 v10, v231, v10
	v_mul_f32_e32 v11, v231, v11
	v_mul_f32_e32 v12, v231, v12
	v_mul_f32_e32 v13, v231, v13
	v_mul_f32_e32 v14, v231, v14
	v_mul_f32_e32 v15, v231, v15
	v_mfma_f32_16x16x32_bf16 v[60:63], v[180:183], v[196:199], v[60:63]
	v_mul_f32_e32 v224, s100, v8
	v_mul_f32_e32 v225, s101, v9
	v_mul_f32_e32 v228, s100, v10
	v_mul_f32_e32 v229, s101, v11
	v_exp_f32_e32 v224, v224
	v_exp_f32_e32 v225, v225
	v_mfma_f32_16x16x32_bf16 v[52:55], v[188:191], v[196:199], v[52:55]
	v_exp_f32_e32 v228, v228
	v_exp_f32_e32 v229, v229
	v_add_f32_e32 v224, 1.0, v224
	v_add_f32_e32 v225, 1.0, v225
	v_add_f32_e32 v228, 1.0, v228
	v_add_f32_e32 v229, 1.0, v229
	v_mfma_f32_16x16x32_bf16 v[40:43], v[146:149], v[200:203], 0
	v_rcp_f32_e32 v224, v224
	v_rcp_f32_e32 v225, v225
	v_rcp_f32_e32 v228, v228
	v_rcp_f32_e32 v229, v229
	v_nop
	v_mul_f32_e32 v8, v224, v8
	v_mfma_f32_16x16x32_bf16 v[32:35], v[158:161], v[200:203], 0
	v_mul_f32_e32 v9, v225, v9
	v_mul_f32_e32 v10, v228, v10
	v_mul_f32_e32 v11, v229, v11
	v_mul_f32_e32 v8, v12, v8
	v_mul_f32_e32 v9, v13, v9
	v_mul_f32_e32 v10, v14, v10
	v_mfma_f32_16x16x32_bf16 v[40:43], v[154:157], v[204:207], v[40:43]
	v_mul_f32_e32 v11, v15, v11
	v_mul_f32_e32 v4, v231, v4
	v_mul_f32_e32 v5, v231, v5
	v_mul_f32_e32 v6, v231, v6
	v_mul_f32_e32 v7, v231, v7
	v_mul_f32_e32 v0, v231, v0
	v_mfma_f32_16x16x32_bf16 v[32:35], v[162:165], v[204:207], v[32:35]
	v_mul_f32_e32 v1, v231, v1
	v_mul_f32_e32 v2, v231, v2
	v_mul_f32_e32 v3, v231, v3
	v_mul_f32_e32 v224, s100, v4
	v_mul_f32_e32 v225, s101, v5
	v_mul_f32_e32 v228, s100, v6
	v_mfma_f32_16x16x32_bf16 v[44:47], v[176:179], v[200:203], 0
	v_mul_f32_e32 v229, s101, v7
	v_exp_f32_e32 v224, v224
	v_exp_f32_e32 v225, v225
	v_exp_f32_e32 v228, v228
	v_exp_f32_e32 v229, v229
	v_add_f32_e32 v224, 1.0, v224
	v_mfma_f32_16x16x32_bf16 v[36:39], v[184:187], v[200:203], 0
	v_add_f32_e32 v225, 1.0, v225
	v_add_f32_e32 v228, 1.0, v228
	v_add_f32_e32 v229, 1.0, v229
	v_rcp_f32_e32 v224, v224
	v_rcp_f32_e32 v225, v225
	v_rcp_f32_e32 v228, v228
	v_mfma_f32_16x16x32_bf16 v[44:47], v[180:183], v[204:207], v[44:47]
	v_rcp_f32_e32 v229, v229
	v_nop
	v_mul_f32_e32 v4, v224, v4
	v_mul_f32_e32 v5, v225, v5
	v_mul_f32_e32 v6, v228, v6
	v_mul_f32_e32 v7, v229, v7
	v_mfma_f32_16x16x32_bf16 v[36:39], v[188:191], v[204:207], v[36:39]
	v_mul_f32_e32 v4, v0, v4
	v_mul_f32_e32 v5, v1, v5
	v_mul_f32_e32 v6, v2, v6
	v_mul_f32_e32 v7, v3, v7
	v_cvt_pk_bf16_f32 v8, v8, v9
	v_cvt_pk_bf16_f32 v9, v10, v11
	s_setprio 0
	s_setprio 1
	v_mfma_f32_16x16x32_bf16 v[24:27], v[146:149], v[208:211], 0
	v_cvt_pk_bf16_f32 v10, v4, v5
	v_cvt_pk_bf16_f32 v11, v6, v7
	global_store_dwordx4 v[232:233], v[8:11], off
	v_mfma_f32_16x16x32_bf16 v[16:19], v[158:161], v[208:211], 0
	v_mfma_f32_16x16x32_bf16 v[24:27], v[154:157], v[212:215], v[24:27]
	v_mfma_f32_16x16x32_bf16 v[16:19], v[162:165], v[212:215], v[16:19]
	v_mfma_f32_16x16x32_bf16 v[28:31], v[176:179], v[208:211], 0
	v_mfma_f32_16x16x32_bf16 v[20:23], v[184:187], v[208:211], 0
	v_mfma_f32_16x16x32_bf16 v[28:31], v[180:183], v[212:215], v[28:31]
	v_mfma_f32_16x16x32_bf16 v[20:23], v[188:191], v[212:215], v[20:23]
	v_mfma_f32_16x16x32_bf16 v[8:11], v[146:149], v[216:219], 0
	v_mfma_f32_16x16x32_bf16 v[4:7], v[158:161], v[216:219], 0
	v_mfma_f32_16x16x32_bf16 v[8:11], v[154:157], v[240:243], v[8:11]
	v_mfma_f32_16x16x32_bf16 v[4:7], v[162:165], v[240:243], v[4:7]
	v_mfma_f32_16x16x32_bf16 v[12:15], v[176:179], v[216:219], 0
	v_mfma_f32_16x16x32_bf16 v[0:3], v[184:187], v[216:219], 0
	v_mfma_f32_16x16x32_bf16 v[12:15], v[180:183], v[240:243], v[12:15]
	v_mfma_f32_16x16x32_bf16 v[0:3], v[188:191], v[240:243], v[0:3]
	s_setprio 0
	s_barrier
	s_add_i32 s10, 0, 0x18000
	v_add_u32_e32 v150, s10, v151
	s_add_i32 s65, 0, 0x1c000
	ds_read_b128 v[146:149], v150
	ds_read_b128 v[154:157], v150 offset:1024
	ds_read_b128 v[158:161], v150 offset:2048
	ds_read_b128 v[162:165], v150 offset:3072
	v_add_u32_e32 v150, s65, v151
	ds_read_b128 v[176:179], v150
	ds_read_b128 v[180:183], v150 offset:1024
	ds_read_b128 v[184:187], v150 offset:2048
	ds_read_b128 v[188:191], v150 offset:3072
	v_lshl_add_u64 v[166:167], v[166:167], 0, s[94:95]
	s_mov_b32 m0, s53
	v_lshl_add_u64 v[252:253], v[166:167], 0, v[132:133]
	ds_read_b128 v[192:195], v153 offset:32768
	ds_read_b128 v[196:199], v153 offset:33792
	ds_read_b128 v[200:203], v153 offset:34816
	ds_read_b128 v[204:207], v153 offset:35840
	ds_read_b128 v[208:211], v153 offset:36864
	ds_read_b128 v[212:215], v153 offset:37888
	ds_read_b128 v[216:219], v153 offset:38912
	ds_read_b128 v[240:243], v153 offset:39936
	global_load_lds_dwordx4 v[252:253], off
	v_lshl_add_u64 v[166:167], v[166:167], 0, v[130:131]
	s_mov_b32 m0, s54
	s_nop 0
	global_load_lds_dwordx4 v[166:167], off
	s_waitcnt vmcnt(12)
	s_waitcnt lgkmcnt(0)
	s_barrier
; #define PG8_STAGE(bufoff, gbase, voff) do { _Pragma("unroll") for (int _i = 0; _i < 2; ++_i) \
;         __builtin_amdgcn_global_load_lds((const unsigned*)((const char*)(gbase) + (voff)[_i]), (LAS unsigned*)(lds + (bufoff) + ldsw + _i * 8192), 16, 0, 0); } while (0)
; #define PG8_LDA(dst, b, h) do { _Pragma("unroll") for (int m = 0; m < 4; ++m) _Pragma("unroll") for (int k = 0; k < 2; ++k) dst[m][k] = *(const LAS bf16x8*)(lds + PG8_SA(b, h) + aoff + m * 2048 + k * 1024); } while (0)
; #define PG8_LDB(dst, b, h) do { _Pragma("unroll") for (int n = 0; n < 2; ++n) _Pragma("unroll") for (int k = 0; k < 2; ++k) dst[n][k] = *(const LAS bf16x8*)(lds + PG8_SB(b, h) + boff + n * 2048 + k * 1024); } while (0)
; #define PG8_MMA(ai, bj, At, Bt) do { __builtin_amdgcn_s_setprio(1); _Pragma("unroll") for (int k = 0; k < 2; ++k) _Pragma("unroll") for (int m = 0; m < 4; ++m) _Pragma("unroll") for (int n = 0; n < 2; ++n) \
;         acc[ai][bj][m][n] = __builtin_amdgcn_mfma_f32_16x16x32_bf16(Bt[n][k], At[m][k], acc[ai][bj][m][n], 0, 0, 0); __builtin_amdgcn_s_setprio(0); } while (0)
; #define PG8_WAIT_V(n) asm volatile("s_waitcnt vmcnt(" #n ")" ::: "memory")
; #define PG8_WAIT_L(n) asm volatile("s_waitcnt lgkmcnt(" #n ")" ::: "memory")
; #define PG8_BAR __builtin_amdgcn_s_barrier()
; #define PG8_SCHED __builtin_amdgcn_sched_barrier(0)
; template <class Epi, bool ALIGN_EPI>
; __device__ __forceinline__ void gemm_phase(LAS unsigned char* lds, const Gemm g, const StaticOrder& S, const Epi& E, const int tid) {
;     ...
;             PG8_LDB(B0, 1, 0); PG8_LDB(B1, 1, 1); PG8_SCHED; PG8_LDA(At, 1, 0); PG8_STAGE(PG8_SA(0, 1), a2 + hA, voffA);
;             PG8_WAIT_V(8); PG8_WAIT_L(0); PG8_BAR; PG8_MMA(0, 0, At, B0); PG8_MMA(0, 1, At, B1); PG8_BAR; PG8_SCHED;
;             PG8_LDA(At, 1, 1); PG8_STAGE(PG8_SB(1, 0), b3, voffB); PG8_STAGE(PG8_SB(1, 1), b3 + hB, voffB); PG8_STAGE(PG8_SA(1, 0), a3, voffA);
;             PG8_WAIT_V(8); PG8_WAIT_L(0); PG8_BAR; PG8_MMA(1, 0, At, B0); PG8_MMA(1, 1, At, B1); PG8_BAR; PG8_SCHED;
	s_setprio 1
	s_waitcnt lgkmcnt(0)
	v_mfma_f32_16x16x32_bf16 v[120:123], v[146:149], v[192:195], v[120:123]
	v_mfma_f32_16x16x32_bf16 v[112:115], v[158:161], v[192:195], v[112:115]
	v_mfma_f32_16x16x32_bf16 v[104:107], v[146:149], v[200:203], v[104:107]
	v_mfma_f32_16x16x32_bf16 v[96:99], v[158:161], v[200:203], v[96:99]
	v_mfma_f32_16x16x32_bf16 v[88:91], v[146:149], v[208:211], v[88:91]
	v_mfma_f32_16x16x32_bf16 v[80:83], v[158:161], v[208:211], v[80:83]
	v_mfma_f32_16x16x32_bf16 v[72:75], v[146:149], v[216:219], v[72:75]
	v_mfma_f32_16x16x32_bf16 v[64:67], v[158:161], v[216:219], v[64:67]
	v_mfma_f32_16x16x32_bf16 v[120:123], v[154:157], v[196:199], v[120:123]
	v_mfma_f32_16x16x32_bf16 v[112:115], v[162:165], v[196:199], v[112:115]
	v_mfma_f32_16x16x32_bf16 v[104:107], v[154:157], v[204:207], v[104:107]
	v_mfma_f32_16x16x32_bf16 v[96:99], v[162:165], v[204:207], v[96:99]
	v_mfma_f32_16x16x32_bf16 v[88:91], v[154:157], v[212:215], v[88:91]
	v_mfma_f32_16x16x32_bf16 v[80:83], v[162:165], v[212:215], v[80:83]
	v_mfma_f32_16x16x32_bf16 v[72:75], v[154:157], v[240:243], v[72:75]
	v_mfma_f32_16x16x32_bf16 v[64:67], v[162:165], v[240:243], v[64:67]
	s_setprio 0
	s_setprio 1
	v_mfma_f32_16x16x32_bf16 v[124:127], v[176:179], v[192:195], v[124:127]
	v_mfma_f32_16x16x32_bf16 v[116:119], v[184:187], v[192:195], v[116:119]
	v_mfma_f32_16x16x32_bf16 v[108:111], v[176:179], v[200:203], v[108:111]
	v_mfma_f32_16x16x32_bf16 v[100:103], v[184:187], v[200:203], v[100:103]
	v_mfma_f32_16x16x32_bf16 v[92:95], v[176:179], v[208:211], v[92:95]
	v_mfma_f32_16x16x32_bf16 v[84:87], v[184:187], v[208:211], v[84:87]
	v_mfma_f32_16x16x32_bf16 v[76:79], v[176:179], v[216:219], v[76:79]
	v_mfma_f32_16x16x32_bf16 v[68:71], v[184:187], v[216:219], v[68:71]
	v_mfma_f32_16x16x32_bf16 v[124:127], v[180:183], v[196:199], v[124:127]
	v_mfma_f32_16x16x32_bf16 v[116:119], v[188:191], v[196:199], v[116:119]
	v_mfma_f32_16x16x32_bf16 v[108:111], v[180:183], v[204:207], v[108:111]
	v_mfma_f32_16x16x32_bf16 v[100:103], v[188:191], v[204:207], v[100:103]
	v_mfma_f32_16x16x32_bf16 v[92:95], v[180:183], v[212:215], v[92:95]
	v_mfma_f32_16x16x32_bf16 v[84:87], v[188:191], v[212:215], v[84:87]
	v_mfma_f32_16x16x32_bf16 v[76:79], v[180:183], v[240:243], v[76:79]
	v_mfma_f32_16x16x32_bf16 v[68:71], v[188:191], v[240:243], v[68:71]
	s_setprio 0
	s_barrier
	s_add_i32 s10, s10, s45
	v_lshl_add_u64 v[166:167], v[226:227], 0, s[92:93]
	s_mov_b32 m0, s10
	ds_read_b128 v[192:195], v153 offset:49152
	ds_read_b128 v[196:199], v153 offset:50176
	ds_read_b128 v[200:203], v153 offset:51200
	ds_read_b128 v[204:207], v153 offset:52224
	ds_read_b128 v[208:211], v153 offset:53248
	ds_read_b128 v[212:215], v153 offset:54272
	ds_read_b128 v[216:219], v153 offset:55296
	ds_read_b128 v[240:243], v153 offset:56320
	global_load_lds_dwordx4 v[166:167], off
	v_lshl_add_u64 v[166:167], v[244:245], 0, s[92:93]
	s_add_i32 m0, s10, 0x2000
	s_add_i32 s10, s65, s45
	global_load_lds_dwordx4 v[166:167], off
	v_lshl_add_u64 v[166:167], v[246:247], 0, s[92:93]
	s_mov_b32 m0, s10
	s_nop 0
	global_load_lds_dwordx4 v[166:167], off
	v_lshl_add_u64 v[166:167], v[220:221], 0, s[92:93]
	s_add_i32 m0, s10, 0x2000
	s_nop 0
	global_load_lds_dwordx4 v[166:167], off
	v_lshl_add_u64 v[166:167], v[248:249], 0, s[92:93]
	s_mov_b32 m0, s56
	s_nop 0
	global_load_lds_dwordx4 v[166:167], off
	v_lshl_add_u64 v[166:167], v[250:251], 0, s[92:93]
	s_mov_b32 m0, s57
	s_nop 0
	global_load_lds_dwordx4 v[166:167], off
	s_waitcnt vmcnt(10)
	s_waitcnt lgkmcnt(0)
	s_barrier
	s_setprio 1
	s_waitcnt lgkmcnt(0)
	v_mfma_f32_16x16x32_bf16 v[56:59], v[146:149], v[192:195], v[56:59]
	v_mfma_f32_16x16x32_bf16 v[48:51], v[158:161], v[192:195], v[48:51]
	v_mfma_f32_16x16x32_bf16 v[40:43], v[146:149], v[200:203], v[40:43]
	v_mfma_f32_16x16x32_bf16 v[32:35], v[158:161], v[200:203], v[32:35]
	v_mfma_f32_16x16x32_bf16 v[24:27], v[146:149], v[208:211], v[24:27]
	v_mfma_f32_16x16x32_bf16 v[16:19], v[158:161], v[208:211], v[16:19]
	v_mfma_f32_16x16x32_bf16 v[8:11], v[146:149], v[216:219], v[8:11]
	v_mfma_f32_16x16x32_bf16 v[4:7], v[158:161], v[216:219], v[4:7]
	v_mfma_f32_16x16x32_bf16 v[56:59], v[154:157], v[196:199], v[56:59]
	v_mfma_f32_16x16x32_bf16 v[48:51], v[162:165], v[196:199], v[48:51]
	v_mfma_f32_16x16x32_bf16 v[40:43], v[154:157], v[204:207], v[40:43]
	v_mfma_f32_16x16x32_bf16 v[32:35], v[162:165], v[204:207], v[32:35]
	v_mfma_f32_16x16x32_bf16 v[24:27], v[154:157], v[212:215], v[24:27]
	v_mfma_f32_16x16x32_bf16 v[16:19], v[162:165], v[212:215], v[16:19]
	v_mfma_f32_16x16x32_bf16 v[8:11], v[154:157], v[240:243], v[8:11]
	v_mfma_f32_16x16x32_bf16 v[4:7], v[162:165], v[240:243], v[4:7]
	s_setprio 0
	s_setprio 1
	v_mfma_f32_16x16x32_bf16 v[60:63], v[176:179], v[192:195], v[60:63]
	v_mfma_f32_16x16x32_bf16 v[52:55], v[184:187], v[192:195], v[52:55]
	v_mfma_f32_16x16x32_bf16 v[44:47], v[176:179], v[200:203], v[44:47]
	v_mfma_f32_16x16x32_bf16 v[36:39], v[184:187], v[200:203], v[36:39]
	v_mfma_f32_16x16x32_bf16 v[28:31], v[176:179], v[208:211], v[28:31]
	v_mfma_f32_16x16x32_bf16 v[20:23], v[184:187], v[208:211], v[20:23]
	v_mfma_f32_16x16x32_bf16 v[12:15], v[176:179], v[216:219], v[12:15]
	v_mfma_f32_16x16x32_bf16 v[0:3], v[184:187], v[216:219], v[0:3]
	v_mfma_f32_16x16x32_bf16 v[60:63], v[180:183], v[196:199], v[60:63]
	v_mfma_f32_16x16x32_bf16 v[52:55], v[188:191], v[196:199], v[52:55]
	v_mfma_f32_16x16x32_bf16 v[44:47], v[180:183], v[204:207], v[44:47]
	v_mfma_f32_16x16x32_bf16 v[36:39], v[188:191], v[204:207], v[36:39]
	v_mfma_f32_16x16x32_bf16 v[28:31], v[180:183], v[212:215], v[28:31]
	v_mfma_f32_16x16x32_bf16 v[20:23], v[188:191], v[212:215], v[20:23]
	v_mfma_f32_16x16x32_bf16 v[12:15], v[180:183], v[240:243], v[12:15]
	v_mfma_f32_16x16x32_bf16 v[0:3], v[188:191], v[240:243], v[0:3]
	s_setprio 0
	s_barrier
	v_lshl_add_u64 v[142:143], v[142:143], 0, s[80:81]
	v_lshl_add_u64 v[144:145], v[144:145], 0, s[80:81]
	s_mov_b32 s10, s11
	s_cmp_eq_u32 s10, s58
	s_cbranch_scc1 .Lgu_last
	s_branch .LBB0_308

; #define PG8_STAGE(bufoff, gbase, voff) do { _Pragma("unroll") for (int _i = 0; _i < 2; ++_i) \
;         __builtin_amdgcn_global_load_lds((const unsigned*)((const char*)(gbase) + (voff)[_i]), (LAS unsigned*)(lds + (bufoff) + ldsw + _i * 8192), 16, 0, 0); } while (0)
; #define PG8_LDA(dst, b, h) do { _Pragma("unroll") for (int m = 0; m < 4; ++m) _Pragma("unroll") for (int k = 0; k < 2; ++k) dst[m][k] = *(const LAS bf16x8*)(lds + PG8_SA(b, h) + aoff + m * 2048 + k * 1024); } while (0)
; #define PG8_LDB(dst, b, h) do { _Pragma("unroll") for (int n = 0; n < 2; ++n) _Pragma("unroll") for (int k = 0; k < 2; ++k) dst[n][k] = *(const LAS bf16x8*)(lds + PG8_SB(b, h) + boff + n * 2048 + k * 1024); } while (0)
; #define PG8_MMA(ai, bj, At, Bt) do { __builtin_amdgcn_s_setprio(1); _Pragma("unroll") for (int k = 0; k < 2; ++k) _Pragma("unroll") for (int m = 0; m < 4; ++m) _Pragma("unroll") for (int n = 0; n < 2; ++n) \
;         acc[ai][bj][m][n] = __builtin_amdgcn_mfma_f32_16x16x32_bf16(Bt[n][k], At[m][k], acc[ai][bj][m][n], 0, 0, 0); __builtin_amdgcn_s_setprio(0); } while (0)
; #define PG8_WAIT_V(n) asm volatile("s_waitcnt vmcnt(" #n ")" ::: "memory")
; #define PG8_WAIT_L(n) asm volatile("s_waitcnt lgkmcnt(" #n ")" ::: "memory")
; #define PG8_BAR __builtin_amdgcn_s_barrier()
; #define PG8_SCHED __builtin_amdgcn_sched_barrier(0)
; template <class Epi, bool ALIGN_EPI>
; __device__ __forceinline__ void gemm_phase(LAS unsigned char* lds, const Gemm g, const StaticOrder& S, const Epi& E, const int tid) {
;     ...
;             const bool last = (t == nt - 2);
;             const char* a1 = cA + (size_t)(t + 1) * kstep;
;             const char* a2 = last ? nA : cA + (size_t)(t + 2) * kstep; const char* b2 = last ? nB : cB + (size_t)(t + 2) * kstep;
;             const char* a3 = a2 + kstep; const char* b3 = b2 + kstep;
;             PG8_LDB(B0, 0, 0); PG8_LDB(B1, 0, 1); PG8_SCHED; PG8_LDA(At, 0, 0); PG8_STAGE(PG8_SA(1, 1), a1 + hA, voffA);
;             PG8_WAIT_V(8); PG8_WAIT_L(0); PG8_BAR; PG8_MMA(0, 0, At, B0); PG8_MMA(0, 1, At, B1); PG8_BAR; PG8_SCHED;
;             PG8_LDA(At, 0, 1); PG8_STAGE(PG8_SB(0, 0), b2, voffB); PG8_STAGE(PG8_SB(0, 1), b2 + hB, voffB); PG8_STAGE(PG8_SA(0, 0), a2, voffA);
.Lgu_last:
	s_add_i32 s11, s10, 2
	s_cmp_eq_u32 s58, s10
	v_lshl_add_u64 v[146:147], v[142:143], 0, s[92:93]
	s_cselect_b64 vcc, -1, 0
	v_add_u32_e32 v150, s33, v151
	s_add_i32 s10, 0, 0x14000
	v_cndmask_b32_e32 v167, v147, v139, vcc
	v_cndmask_b32_e32 v166, v146, v138, vcc
	ds_read_b128 v[146:149], v150
	ds_read_b128 v[154:157], v150 offset:1024
	ds_read_b128 v[158:161], v150 offset:2048
	ds_read_b128 v[162:165], v150 offset:3072
	v_add_u32_e32 v150, s10, v151
	ds_read_b128 v[176:179], v150
	ds_read_b128 v[180:183], v150 offset:1024
	ds_read_b128 v[184:187], v150 offset:2048
	ds_read_b128 v[188:191], v150 offset:3072
	v_cndmask_b32_e32 v221, v145, v141, vcc
	v_cndmask_b32_e32 v220, v144, v140, vcc
	v_lshl_add_u64 v[226:227], v[142:143], 0, v[134:135]
	s_add_i32 m0, s51, 0xc000
	ds_read_b128 v[192:195], v153
	ds_read_b128 v[196:199], v153 offset:1024
	ds_read_b128 v[200:203], v153 offset:2048
	ds_read_b128 v[204:207], v153 offset:3072
	ds_read_b128 v[208:211], v153 offset:4096
	ds_read_b128 v[212:215], v153 offset:5120
	ds_read_b128 v[216:219], v153 offset:6144
	ds_read_b128 v[240:243], v153 offset:7168
	global_load_lds_dwordx4 v[226:227], off
	v_lshl_add_u64 v[226:227], v[142:143], 0, v[136:137]
	s_add_i32 m0, s51, 0xe000
	s_nop 0
	global_load_lds_dwordx4 v[226:227], off
	s_waitcnt vmcnt(8)
	s_waitcnt lgkmcnt(0)
	s_barrier
	s_setprio 1
	s_waitcnt lgkmcnt(0)
	v_mfma_f32_16x16x32_bf16 v[120:123], v[146:149], v[192:195], v[120:123]
	v_mfma_f32_16x16x32_bf16 v[112:115], v[158:161], v[192:195], v[112:115]
	v_mfma_f32_16x16x32_bf16 v[104:107], v[146:149], v[200:203], v[104:107]
	v_mfma_f32_16x16x32_bf16 v[96:99], v[158:161], v[200:203], v[96:99]
	v_mfma_f32_16x16x32_bf16 v[88:91], v[146:149], v[208:211], v[88:91]
	v_mfma_f32_16x16x32_bf16 v[80:83], v[158:161], v[208:211], v[80:83]
	v_mfma_f32_16x16x32_bf16 v[72:75], v[146:149], v[216:219], v[72:75]
	v_mfma_f32_16x16x32_bf16 v[64:67], v[158:161], v[216:219], v[64:67]
	v_mfma_f32_16x16x32_bf16 v[120:123], v[154:157], v[196:199], v[120:123]
	v_mfma_f32_16x16x32_bf16 v[112:115], v[162:165], v[196:199], v[112:115]
	v_mfma_f32_16x16x32_bf16 v[104:107], v[154:157], v[204:207], v[104:107]
	v_mfma_f32_16x16x32_bf16 v[96:99], v[162:165], v[204:207], v[96:99]
	v_mfma_f32_16x16x32_bf16 v[88:91], v[154:157], v[212:215], v[88:91]
	v_mfma_f32_16x16x32_bf16 v[80:83], v[162:165], v[212:215], v[80:83]
	v_mfma_f32_16x16x32_bf16 v[72:75], v[154:157], v[240:243], v[72:75]
	v_mfma_f32_16x16x32_bf16 v[64:67], v[162:165], v[240:243], v[64:67]
	s_setprio 0
	s_setprio 1
	v_mfma_f32_16x16x32_bf16 v[124:127], v[176:179], v[192:195], v[124:127]
	v_mfma_f32_16x16x32_bf16 v[116:119], v[184:187], v[192:195], v[116:119]
	v_mfma_f32_16x16x32_bf16 v[108:111], v[176:179], v[200:203], v[108:111]
	v_mfma_f32_16x16x32_bf16 v[100:103], v[184:187], v[200:203], v[100:103]
	v_mfma_f32_16x16x32_bf16 v[92:95], v[176:179], v[208:211], v[92:95]
	v_mfma_f32_16x16x32_bf16 v[84:87], v[184:187], v[208:211], v[84:87]
	v_mfma_f32_16x16x32_bf16 v[76:79], v[176:179], v[216:219], v[76:79]
	v_mfma_f32_16x16x32_bf16 v[68:71], v[184:187], v[216:219], v[68:71]
	v_mfma_f32_16x16x32_bf16 v[124:127], v[180:183], v[196:199], v[124:127]
	v_mfma_f32_16x16x32_bf16 v[116:119], v[188:191], v[196:199], v[116:119]
	v_mfma_f32_16x16x32_bf16 v[108:111], v[180:183], v[204:207], v[108:111]
	v_mfma_f32_16x16x32_bf16 v[100:103], v[188:191], v[204:207], v[100:103]
	v_mfma_f32_16x16x32_bf16 v[92:95], v[180:183], v[212:215], v[92:95]
	v_mfma_f32_16x16x32_bf16 v[84:87], v[188:191], v[212:215], v[84:87]
	v_mfma_f32_16x16x32_bf16 v[76:79], v[180:183], v[240:243], v[76:79]
	v_mfma_f32_16x16x32_bf16 v[68:71], v[188:191], v[240:243], v[68:71]
	s_setprio 0
	s_barrier
	s_add_i32 s65, s33, s45
	v_lshl_add_u64 v[226:227], v[220:221], 0, v[168:169]
	s_mov_b32 m0, s65
	ds_read_b128 v[192:195], v153 offset:16384
	ds_read_b128 v[196:199], v153 offset:17408
	ds_read_b128 v[200:203], v153 offset:18432
	ds_read_b128 v[204:207], v153 offset:19456
	ds_read_b128 v[208:211], v153 offset:20480
	ds_read_b128 v[212:215], v153 offset:21504
	ds_read_b128 v[216:219], v153 offset:22528
	ds_read_b128 v[240:243], v153 offset:23552
	global_load_lds_dwordx4 v[226:227], off
	v_lshl_add_u64 v[244:245], v[220:221], 0, v[128:129]
	s_add_i32 m0, s65, 0x2000
	v_lshl_add_u64 v[220:221], v[220:221], 0, s[12:13]
	s_add_i32 s10, s10, s45
	global_load_lds_dwordx4 v[244:245], off
	v_lshl_add_u64 v[246:247], v[220:221], 0, v[168:169]
	s_mov_b32 m0, s10
	v_lshl_add_u64 v[220:221], v[220:221], 0, v[128:129]
	global_load_lds_dwordx4 v[246:247], off
	s_add_i32 m0, s10, 0x2000
	v_lshl_add_u64 v[248:249], v[166:167], 0, v[132:133]
	global_load_lds_dwordx4 v[220:221], off
	s_mov_b32 m0, s51
	v_lshl_add_u64 v[250:251], v[166:167], 0, v[130:131]
	global_load_lds_dwordx4 v[248:249], off
	s_mov_b32 m0, s52
	s_nop 0
	global_load_lds_dwordx4 v[250:251], off
	s_waitcnt vmcnt(8)
	s_waitcnt lgkmcnt(0)
	s_barrier
; __device__ __forceinline__ float siluf_(float x) { return x * sigmoidf_(x); }
; #define PG8_STAGE(bufoff, gbase, voff) do { _Pragma("unroll") for (int _i = 0; _i < 2; ++_i) \
;         __builtin_amdgcn_global_load_lds((const unsigned*)((const char*)(gbase) + (voff)[_i]), (LAS unsigned*)(lds + (bufoff) + ldsw + _i * 8192), 16, 0, 0); } while (0)
; #define PG8_LDA(dst, b, h) do { _Pragma("unroll") for (int m = 0; m < 4; ++m) _Pragma("unroll") for (int k = 0; k < 2; ++k) dst[m][k] = *(const LAS bf16x8*)(lds + PG8_SA(b, h) + aoff + m * 2048 + k * 1024); } while (0)
; #define PG8_MMA(ai, bj, At, Bt) do { __builtin_amdgcn_s_setprio(1); _Pragma("unroll") for (int k = 0; k < 2; ++k) _Pragma("unroll") for (int m = 0; m < 4; ++m) _Pragma("unroll") for (int n = 0; n < 2; ++n) \
;         acc[ai][bj][m][n] = __builtin_amdgcn_mfma_f32_16x16x32_bf16(Bt[n][k], At[m][k], acc[ai][bj][m][n], 0, 0, 0); __builtin_amdgcn_s_setprio(0); } while (0)
; #define PG8_WAIT_V(n) asm volatile("s_waitcnt vmcnt(" #n ")" ::: "memory")
; #define PG8_BAR __builtin_amdgcn_s_barrier()
;     __device__ __forceinline__ void operator()(const f32x4 (&acc)[2][2][4][2], const Unit& u, int wr, int wc, int fr, int fq) const {
;         const int row0 = u.pm * BM + wr * 64 + fr, col0 = u.pn * HALF + wc * 32 + 8 * fq;
;         float rsv[2][4]; load_rstd(rsv, ssq, row0);
; #pragma unroll
;         for (int ai = 0; ai < 2; ++ai)
; #pragma unroll
;             for (int m = 0; m < 4; ++m) { const int row = row0 + ai * HALF + m * 16; bf16_t* rowp = O + (size_t)row * ldc + col0; const float rs = rsv[ai][m];
;                 f32x4 v0, v1;
; #pragma unroll
;                 for (int j = 0; j < 4; ++j) { v0[j] = siluf_(acc[ai][0][m][0][j] * rs) * (acc[ai][1][m][0][j] * rs); v1[j] = siluf_(acc[ai][0][m][1][j] * rs) * (acc[ai][1][m][1][j] * rs); }
; template <class Epi, bool ALIGN_EPI>
; __device__ __forceinline__ void gemm_phase(LAS unsigned char* lds, const Gemm g, const StaticOrder& S, const Epi& E, const int tid) {
;     ...
;             PG8_WAIT_V(8); PG8_WAIT_L(0); PG8_BAR; PG8_MMA(0, 0, At, B0); PG8_MMA(0, 1, At, B1); PG8_BAR; PG8_SCHED;
;             PG8_LDA(At, 1, 1); PG8_STAGE(PG8_SB(1, 0), b3, voffB); PG8_STAGE(PG8_SB(1, 1), b3 + hB, voffB); PG8_STAGE(PG8_SA(1, 0), a3, voffA);
;             PG8_WAIT_V(8); PG8_WAIT_L(0); PG8_BAR; PG8_MMA(1, 0, At, B0); PG8_MMA(1, 1, At, B1); PG8_BAR; PG8_SCHED;
	s_setprio 1
	s_waitcnt lgkmcnt(0)
	v_mfma_f32_16x16x32_bf16 v[56:59], v[146:149], v[192:195], v[56:59]
	v_mfma_f32_16x16x32_bf16 v[48:51], v[158:161], v[192:195], v[48:51]
	v_mfma_f32_16x16x32_bf16 v[40:43], v[146:149], v[200:203], v[40:43]
	v_mfma_f32_16x16x32_bf16 v[32:35], v[158:161], v[200:203], v[32:35]
	v_mfma_f32_16x16x32_bf16 v[24:27], v[146:149], v[208:211], v[24:27]
	v_mfma_f32_16x16x32_bf16 v[16:19], v[158:161], v[208:211], v[16:19]
	v_mfma_f32_16x16x32_bf16 v[8:11], v[146:149], v[216:219], v[8:11]
	v_mfma_f32_16x16x32_bf16 v[4:7], v[158:161], v[216:219], v[4:7]
	v_mfma_f32_16x16x32_bf16 v[56:59], v[154:157], v[196:199], v[56:59]
	v_mfma_f32_16x16x32_bf16 v[48:51], v[162:165], v[196:199], v[48:51]
	v_mfma_f32_16x16x32_bf16 v[40:43], v[154:157], v[204:207], v[40:43]
	v_mfma_f32_16x16x32_bf16 v[32:35], v[162:165], v[204:207], v[32:35]
	v_mfma_f32_16x16x32_bf16 v[24:27], v[154:157], v[212:215], v[24:27]
	v_mfma_f32_16x16x32_bf16 v[16:19], v[162:165], v[212:215], v[16:19]
	v_mfma_f32_16x16x32_bf16 v[8:11], v[154:157], v[240:243], v[8:11]
	v_mfma_f32_16x16x32_bf16 v[4:7], v[162:165], v[240:243], v[4:7]
	s_setprio 0
	s_setprio 1
	v_mfma_f32_16x16x32_bf16 v[60:63], v[176:179], v[192:195], v[60:63]
	v_mfma_f32_16x16x32_bf16 v[52:55], v[184:187], v[192:195], v[52:55]
	v_mfma_f32_16x16x32_bf16 v[44:47], v[176:179], v[200:203], v[44:47]
	v_mfma_f32_16x16x32_bf16 v[36:39], v[184:187], v[200:203], v[36:39]
	v_mfma_f32_16x16x32_bf16 v[28:31], v[176:179], v[208:211], v[28:31]
	v_mfma_f32_16x16x32_bf16 v[20:23], v[184:187], v[208:211], v[20:23]
	v_mfma_f32_16x16x32_bf16 v[12:15], v[176:179], v[216:219], v[12:15]
	v_mfma_f32_16x16x32_bf16 v[0:3], v[184:187], v[216:219], v[0:3]
	v_mfma_f32_16x16x32_bf16 v[60:63], v[180:183], v[196:199], v[60:63]
	v_mfma_f32_16x16x32_bf16 v[52:55], v[188:191], v[196:199], v[52:55]
	v_mfma_f32_16x16x32_bf16 v[44:47], v[180:183], v[204:207], v[44:47]
	v_mfma_f32_16x16x32_bf16 v[36:39], v[188:191], v[204:207], v[36:39]
	v_mfma_f32_16x16x32_bf16 v[28:31], v[180:183], v[212:215], v[28:31]
	v_mfma_f32_16x16x32_bf16 v[20:23], v[188:191], v[212:215], v[20:23]
	v_mfma_f32_16x16x32_bf16 v[12:15], v[180:183], v[240:243], v[12:15]
	v_mfma_f32_16x16x32_bf16 v[0:3], v[188:191], v[240:243], v[0:3]
	s_setprio 0
	s_barrier
	s_add_i32 s10, 0, 0x18000
	v_add_u32_e32 v150, s10, v151
	s_add_i32 s65, 0, 0x1c000
	ds_read_b128 v[146:149], v150
	ds_read_b128 v[154:157], v150 offset:1024
	ds_read_b128 v[158:161], v150 offset:2048
	ds_read_b128 v[162:165], v150 offset:3072
	v_add_u32_e32 v150, s65, v151
	ds_read_b128 v[176:179], v150
	ds_read_b128 v[180:183], v150 offset:1024
	ds_read_b128 v[184:187], v150 offset:2048
	ds_read_b128 v[188:191], v150 offset:3072
	v_lshl_add_u64 v[166:167], v[166:167], 0, s[94:95]
	s_mov_b32 m0, s53
	v_lshl_add_u64 v[252:253], v[166:167], 0, v[132:133]
	ds_read_b128 v[192:195], v153 offset:32768
	ds_read_b128 v[196:199], v153 offset:33792
	ds_read_b128 v[200:203], v153 offset:34816
	ds_read_b128 v[204:207], v153 offset:35840
	ds_read_b128 v[208:211], v153 offset:36864
	ds_read_b128 v[212:215], v153 offset:37888
	ds_read_b128 v[216:219], v153 offset:38912
	ds_read_b128 v[240:243], v153 offset:39936
	global_load_lds_dwordx4 v[252:253], off
	v_lshl_add_u64 v[166:167], v[166:167], 0, v[130:131]
	s_mov_b32 m0, s54
	s_nop 0
	global_load_lds_dwordx4 v[166:167], off
	s_waitcnt vmcnt(8)
	s_waitcnt lgkmcnt(0)
	s_barrier
	s_setprio 1
	s_waitcnt lgkmcnt(0)
	v_mfma_f32_16x16x32_bf16 v[120:123], v[146:149], v[192:195], v[120:123]
	v_mfma_f32_16x16x32_bf16 v[112:115], v[158:161], v[192:195], v[112:115]
	v_mfma_f32_16x16x32_bf16 v[120:123], v[154:157], v[196:199], v[120:123]
	v_mfma_f32_16x16x32_bf16 v[112:115], v[162:165], v[196:199], v[112:115]
	v_mfma_f32_16x16x32_bf16 v[124:127], v[176:179], v[192:195], v[124:127]
	v_mfma_f32_16x16x32_bf16 v[116:119], v[184:187], v[192:195], v[116:119]
	v_mfma_f32_16x16x32_bf16 v[124:127], v[180:183], v[196:199], v[124:127]
	v_mfma_f32_16x16x32_bf16 v[116:119], v[188:191], v[196:199], v[116:119]
	v_mfma_f32_16x16x32_bf16 v[104:107], v[146:149], v[200:203], v[104:107]
	v_mfma_f32_16x16x32_bf16 v[96:99], v[158:161], v[200:203], v[96:99]
	v_mfma_f32_16x16x32_bf16 v[104:107], v[154:157], v[204:207], v[104:107]
	v_lshrrev_b32_e32 v171, 8, v170
	v_and_b32_e32 v234, 15, v170
	v_lshl_add_u32 v171, v171, 6, v234
	s_lshl_b32 s98, s64, 8
	v_add_u32_e32 v171, s98, v171
	v_mul_lo_u32 v171, v171, s28
	v_mfma_f32_16x16x32_bf16 v[96:99], v[162:165], v[204:207], v[96:99]
	v_bfe_u32 v234, v170, 6, 2
	v_bfe_u32 v224, v170, 4, 2
	v_lshlrev_b32_e32 v234, 5, v234
	v_lshl_or_b32 v234, v224, 3, v234
	s_lshl_b32 s98, s63, 7
	v_add_u32_e32 v234, s98, v234
	v_mfma_f32_16x16x32_bf16 v[108:111], v[176:179], v[200:203], v[108:111]
	v_add_lshl_u32 v232, v171, v234, 1
	v_mov_b32_e32 v233, 0
	v_lshl_add_u64 v[232:233], v[232:233], 0, s[30:31]
	s_lshl_b32 s98, s28, 5
	s_mov_b32 s99, 0
	s_mov_b32 s100, 0xbfb8aa3b
	v_mfma_f32_16x16x32_bf16 v[100:103], v[184:187], v[200:203], v[100:103]
	s_mov_b32 s101, 0xbfb8aa3b
	v_mul_f32_e32 v120, v172, v120
	v_mul_f32_e32 v121, v172, v121
	v_mul_f32_e32 v122, v172, v122
	v_mul_f32_e32 v123, v172, v123
	v_mul_f32_e32 v124, v172, v124
	v_mfma_f32_16x16x32_bf16 v[108:111], v[180:183], v[204:207], v[108:111]
	v_mul_f32_e32 v125, v172, v125
	v_mul_f32_e32 v126, v172, v126
	v_mul_f32_e32 v127, v172, v127
	v_mul_f32_e32 v224, s100, v120
	v_mul_f32_e32 v225, s101, v121
	v_mul_f32_e32 v228, s100, v122
	v_mfma_f32_16x16x32_bf16 v[100:103], v[188:191], v[204:207], v[100:103]
	v_mul_f32_e32 v229, s101, v123
	v_exp_f32_e32 v224, v224
	v_exp_f32_e32 v225, v225
	v_exp_f32_e32 v228, v228
; __device__ __forceinline__ unsigned cvt_pk_bf16(float lo, float hi) { unsigned r; asm volatile("v_cvt_pk_bf16_f32 %0, %1, %2" : "=v"(r) : "v"(lo), "v"(hi)); return r; }
; __device__ __forceinline__ float siluf_(float x) { return x * sigmoidf_(x); }
; #define PG8_STAGE(bufoff, gbase, voff) do { _Pragma("unroll") for (int _i = 0; _i < 2; ++_i) \
;         __builtin_amdgcn_global_load_lds((const unsigned*)((const char*)(gbase) + (voff)[_i]), (LAS unsigned*)(lds + (bufoff) + ldsw + _i * 8192), 16, 0, 0); } while (0)
; #define PG8_LDA(dst, b, h) do { _Pragma("unroll") for (int m = 0; m < 4; ++m) _Pragma("unroll") for (int k = 0; k < 2; ++k) dst[m][k] = *(const LAS bf16x8*)(lds + PG8_SA(b, h) + aoff + m * 2048 + k * 1024); } while (0)
; #define PG8_MMA(ai, bj, At, Bt) do { __builtin_amdgcn_s_setprio(1); _Pragma("unroll") for (int k = 0; k < 2; ++k) _Pragma("unroll") for (int m = 0; m < 4; ++m) _Pragma("unroll") for (int n = 0; n < 2; ++n) \
;         acc[ai][bj][m][n] = __builtin_amdgcn_mfma_f32_16x16x32_bf16(Bt[n][k], At[m][k], acc[ai][bj][m][n], 0, 0, 0); __builtin_amdgcn_s_setprio(0); } while (0)
; #define PG8_WAIT_V(n) asm volatile("s_waitcnt vmcnt(" #n ")" ::: "memory")
;     __device__ __forceinline__ void operator()(const f32x4 (&acc)[2][2][4][2], const Unit& u, int wr, int wc, int fr, int fq) const {
;     ...
;             for (int m = 0; m < 4; ++m) { const int row = row0 + ai * HALF + m * 16; bf16_t* rowp = O + (size_t)row * ldc + col0; const float rs = rsv[ai][m];
;                 f32x4 v0, v1;
; #pragma unroll
;                 for (int j = 0; j < 4; ++j) { v0[j] = siluf_(acc[ai][0][m][0][j] * rs) * (acc[ai][1][m][0][j] * rs); v1[j] = siluf_(acc[ai][0][m][1][j] * rs) * (acc[ai][1][m][1][j] * rs); }
;                 u32x4 w; w.x = cvt_pk_bf16(v0[0], v0[1]); w.y = cvt_pk_bf16(v0[2], v0[3]); w.z = cvt_pk_bf16(v1[0], v1[1]); w.w = cvt_pk_bf16(v1[2], v1[3]);
;                 *(u32x4*)rowp = w; }
; template <class Epi, bool ALIGN_EPI>
; __device__ __forceinline__ void gemm_phase(LAS unsigned char* lds, const Gemm g, const StaticOrder& S, const Epi& E, const int tid) {
;     ...
;             PG8_LDA(At, 1, 1); PG8_STAGE(PG8_SB(1, 0), b3, voffB); PG8_STAGE(PG8_SB(1, 1), b3 + hB, voffB); PG8_STAGE(PG8_SA(1, 0), a3, voffA);
;             PG8_WAIT_V(8); PG8_WAIT_L(0); PG8_BAR; PG8_MMA(1, 0, At, B0); PG8_MMA(1, 1, At, B1); PG8_BAR; PG8_SCHED;
	v_exp_f32_e32 v229, v229
	v_add_f32_e32 v224, 1.0, v224
	s_setprio 0
	s_setprio 1
	v_mfma_f32_16x16x32_bf16 v[88:91], v[146:149], v[208:211], v[88:91]
	v_add_f32_e32 v225, 1.0, v225
	v_add_f32_e32 v228, 1.0, v228
	v_add_f32_e32 v229, 1.0, v229
	v_rcp_f32_e32 v224, v224
	v_rcp_f32_e32 v225, v225
	v_rcp_f32_e32 v228, v228
	v_mfma_f32_16x16x32_bf16 v[80:83], v[158:161], v[208:211], v[80:83]
	v_rcp_f32_e32 v229, v229
	v_nop
	v_mul_f32_e32 v120, v224, v120
	v_mul_f32_e32 v121, v225, v121
	v_mul_f32_e32 v122, v228, v122
	v_mul_f32_e32 v123, v229, v123
	v_mfma_f32_16x16x32_bf16 v[88:91], v[154:157], v[212:215], v[88:91]
	v_mul_f32_e32 v120, v124, v120
	v_mul_f32_e32 v121, v125, v121
	v_mul_f32_e32 v122, v126, v122
	v_mul_f32_e32 v123, v127, v123
	v_mul_f32_e32 v112, v172, v112
	v_mul_f32_e32 v113, v172, v113
	v_mfma_f32_16x16x32_bf16 v[80:83], v[162:165], v[212:215], v[80:83]
	v_mul_f32_e32 v114, v172, v114
	v_mul_f32_e32 v115, v172, v115
	v_mul_f32_e32 v116, v172, v116
	v_mul_f32_e32 v117, v172, v117
	v_mul_f32_e32 v118, v172, v118
	v_mul_f32_e32 v119, v172, v119
	v_mfma_f32_16x16x32_bf16 v[92:95], v[176:179], v[208:211], v[92:95]
	v_mul_f32_e32 v224, s100, v112
	v_mul_f32_e32 v225, s101, v113
	v_mul_f32_e32 v228, s100, v114
	v_mul_f32_e32 v229, s101, v115
	v_exp_f32_e32 v224, v224
	v_exp_f32_e32 v225, v225
	v_mfma_f32_16x16x32_bf16 v[84:87], v[184:187], v[208:211], v[84:87]
	v_exp_f32_e32 v228, v228
	v_exp_f32_e32 v229, v229
	v_add_f32_e32 v224, 1.0, v224
	v_add_f32_e32 v225, 1.0, v225
	v_add_f32_e32 v228, 1.0, v228
	v_add_f32_e32 v229, 1.0, v229
	v_mfma_f32_16x16x32_bf16 v[92:95], v[180:183], v[212:215], v[92:95]
	v_rcp_f32_e32 v224, v224
	v_rcp_f32_e32 v225, v225
	v_rcp_f32_e32 v228, v228
	v_rcp_f32_e32 v229, v229
	v_nop
	v_mul_f32_e32 v112, v224, v112
	v_mfma_f32_16x16x32_bf16 v[84:87], v[188:191], v[212:215], v[84:87]
	v_mul_f32_e32 v113, v225, v113
	v_mul_f32_e32 v114, v228, v114
	v_mul_f32_e32 v115, v229, v115
	v_mul_f32_e32 v112, v116, v112
	v_mul_f32_e32 v113, v117, v113
	v_mul_f32_e32 v114, v118, v114
	v_mfma_f32_16x16x32_bf16 v[72:75], v[146:149], v[216:219], v[72:75]
	v_mul_f32_e32 v115, v119, v115
	v_cvt_pk_bf16_f32 v120, v120, v121
	v_cvt_pk_bf16_f32 v121, v122, v123
	v_cvt_pk_bf16_f32 v122, v112, v113
	v_cvt_pk_bf16_f32 v123, v114, v115
	global_store_dwordx4 v[232:233], v[120:123], off
	v_mfma_f32_16x16x32_bf16 v[64:67], v[158:161], v[216:219], v[64:67]
	v_lshl_add_u64 v[232:233], v[232:233], 0, s[98:99]
	v_mul_f32_e32 v104, v173, v104
	v_mul_f32_e32 v105, v173, v105
	v_mul_f32_e32 v106, v173, v106
	v_mul_f32_e32 v107, v173, v107
	v_mul_f32_e32 v108, v173, v108
	v_mfma_f32_16x16x32_bf16 v[72:75], v[154:157], v[240:243], v[72:75]
	v_mul_f32_e32 v109, v173, v109
	v_mul_f32_e32 v110, v173, v110
	v_mul_f32_e32 v111, v173, v111
	v_mul_f32_e32 v224, s100, v104
	v_mul_f32_e32 v225, s101, v105
	v_mul_f32_e32 v228, s100, v106
	v_mfma_f32_16x16x32_bf16 v[64:67], v[162:165], v[240:243], v[64:67]
	v_mul_f32_e32 v229, s101, v107
	v_exp_f32_e32 v224, v224
	v_exp_f32_e32 v225, v225
	v_exp_f32_e32 v228, v228
	v_exp_f32_e32 v229, v229
	v_add_f32_e32 v224, 1.0, v224
	v_mfma_f32_16x16x32_bf16 v[76:79], v[176:179], v[216:219], v[76:79]
	v_add_f32_e32 v225, 1.0, v225
	v_add_f32_e32 v228, 1.0, v228
	v_add_f32_e32 v229, 1.0, v229
	v_rcp_f32_e32 v224, v224
	v_rcp_f32_e32 v225, v225
	v_rcp_f32_e32 v228, v228
	v_mfma_f32_16x16x32_bf16 v[68:71], v[184:187], v[216:219], v[68:71]
	v_rcp_f32_e32 v229, v229
	v_nop
	v_mul_f32_e32 v104, v224, v104
	v_mul_f32_e32 v105, v225, v105
	v_mul_f32_e32 v106, v228, v106
	v_mul_f32_e32 v107, v229, v107
	v_mfma_f32_16x16x32_bf16 v[76:79], v[180:183], v[240:243], v[76:79]
	v_mul_f32_e32 v104, v108, v104
	v_mul_f32_e32 v105, v109, v105
	v_mul_f32_e32 v106, v110, v106
	v_mul_f32_e32 v107, v111, v107
	v_mul_f32_e32 v96, v173, v96
	v_mul_f32_e32 v97, v173, v97
	v_mfma_f32_16x16x32_bf16 v[68:71], v[188:191], v[240:243], v[68:71]
	v_mul_f32_e32 v98, v173, v98
	v_mul_f32_e32 v99, v173, v99
	v_mul_f32_e32 v100, v173, v100
	v_mul_f32_e32 v101, v173, v101
	v_mul_f32_e32 v102, v173, v102
	v_mul_f32_e32 v103, v173, v103
	s_setprio 0
	s_barrier
	s_add_i32 s10, s10, s45
	v_lshl_add_u64 v[166:167], v[226:227], 0, s[92:93]
	s_mov_b32 m0, s10
	ds_read_b128 v[192:195], v153 offset:49152
	ds_read_b128 v[196:199], v153 offset:50176
	ds_read_b128 v[200:203], v153 offset:51200
	ds_read_b128 v[204:207], v153 offset:52224
	ds_read_b128 v[208:211], v153 offset:53248
	ds_read_b128 v[212:215], v153 offset:54272
	ds_read_b128 v[216:219], v153 offset:55296
	ds_read_b128 v[240:243], v153 offset:56320
	global_load_lds_dwordx4 v[166:167], off
	v_lshl_add_u64 v[166:167], v[244:245], 0, s[92:93]
	s_add_i32 m0, s10, 0x2000
	s_add_i32 s10, s65, s45
	global_load_lds_dwordx4 v[166:167], off
	v_lshl_add_u64 v[166:167], v[246:247], 0, s[92:93]
	s_mov_b32 m0, s10
	s_nop 0
	global_load_lds_dwordx4 v[166:167], off
	v_lshl_add_u64 v[166:167], v[220:221], 0, s[92:93]
	s_add_i32 m0, s10, 0x2000
	s_nop 0
	global_load_lds_dwordx4 v[166:167], off
	v_lshl_add_u64 v[166:167], v[248:249], 0, s[92:93]
	s_mov_b32 m0, s56
	s_nop 0
	global_load_lds_dwordx4 v[166:167], off
	v_lshl_add_u64 v[166:167], v[250:251], 0, s[92:93]
	s_mov_b32 m0, s57
	s_nop 0
	global_load_lds_dwordx4 v[166:167], off
	s_waitcnt vmcnt(9)
	s_waitcnt lgkmcnt(0)
	s_barrier
; __device__ __forceinline__ unsigned cvt_pk_bf16(float lo, float hi) { unsigned r; asm volatile("v_cvt_pk_bf16_f32 %0, %1, %2" : "=v"(r) : "v"(lo), "v"(hi)); return r; }
; __device__ __forceinline__ float siluf_(float x) { return x * sigmoidf_(x); }
; #define PG8_MMA(ai, bj, At, Bt) do { __builtin_amdgcn_s_setprio(1); _Pragma("unroll") for (int k = 0; k < 2; ++k) _Pragma("unroll") for (int m = 0; m < 4; ++m) _Pragma("unroll") for (int n = 0; n < 2; ++n) \
;         acc[ai][bj][m][n] = __builtin_amdgcn_mfma_f32_16x16x32_bf16(Bt[n][k], At[m][k], acc[ai][bj][m][n], 0, 0, 0); __builtin_amdgcn_s_setprio(0); } while (0)
; #define PG8_WAIT_V(n) asm volatile("s_waitcnt vmcnt(" #n ")" ::: "memory")
; #define PG8_WAIT_L(n) asm volatile("s_waitcnt lgkmcnt(" #n ")" ::: "memory")
; #define PG8_BAR __builtin_amdgcn_s_barrier()
; #define PG8_SCHED __builtin_amdgcn_sched_barrier(0)
;     __device__ __forceinline__ void operator()(const f32x4 (&acc)[2][2][4][2], const Unit& u, int wr, int wc, int fr, int fq) const {
;     ...
;             for (int m = 0; m < 4; ++m) { const int row = row0 + ai * HALF + m * 16; bf16_t* rowp = O + (size_t)row * ldc + col0; const float rs = rsv[ai][m];
;                 f32x4 v0, v1;
; #pragma unroll
;                 for (int j = 0; j < 4; ++j) { v0[j] = siluf_(acc[ai][0][m][0][j] * rs) * (acc[ai][1][m][0][j] * rs); v1[j] = siluf_(acc[ai][0][m][1][j] * rs) * (acc[ai][1][m][1][j] * rs); }
;                 u32x4 w; w.x = cvt_pk_bf16(v0[0], v0[1]); w.y = cvt_pk_bf16(v0[2], v0[3]); w.z = cvt_pk_bf16(v1[0], v1[1]); w.w = cvt_pk_bf16(v1[2], v1[3]);
;                 *(u32x4*)rowp = w; }
; template <class Epi, bool ALIGN_EPI>
; __device__ __forceinline__ void gemm_phase(LAS unsigned char* lds, const Gemm g, const StaticOrder& S, const Epi& E, const int tid) {
;     ...
;             PG8_WAIT_V(8); PG8_WAIT_L(0); PG8_BAR; PG8_MMA(1, 0, At, B0); PG8_MMA(1, 1, At, B1); PG8_BAR; PG8_SCHED;
	s_setprio 1
	s_waitcnt lgkmcnt(0)
	v_mfma_f32_16x16x32_bf16 v[56:59], v[146:149], v[192:195], v[56:59]
	v_mul_f32_e32 v224, s100, v96
	v_mul_f32_e32 v225, s101, v97
	v_mul_f32_e32 v228, s100, v98
	v_mul_f32_e32 v229, s101, v99
	v_exp_f32_e32 v224, v224
	v_exp_f32_e32 v225, v225
	v_mfma_f32_16x16x32_bf16 v[48:51], v[158:161], v[192:195], v[48:51]
	v_exp_f32_e32 v228, v228
	v_exp_f32_e32 v229, v229
	v_add_f32_e32 v224, 1.0, v224
	v_add_f32_e32 v225, 1.0, v225
	v_add_f32_e32 v228, 1.0, v228
	v_add_f32_e32 v229, 1.0, v229
	v_mfma_f32_16x16x32_bf16 v[40:43], v[146:149], v[200:203], v[40:43]
	v_rcp_f32_e32 v224, v224
	v_rcp_f32_e32 v225, v225
	v_rcp_f32_e32 v228, v228
	v_rcp_f32_e32 v229, v229
	v_nop
	v_mul_f32_e32 v96, v224, v96
	v_mfma_f32_16x16x32_bf16 v[32:35], v[158:161], v[200:203], v[32:35]
	v_mul_f32_e32 v97, v225, v97
	v_mul_f32_e32 v98, v228, v98
	v_mul_f32_e32 v99, v229, v99
	v_mul_f32_e32 v96, v100, v96
	v_mul_f32_e32 v97, v101, v97
	v_mul_f32_e32 v98, v102, v98
	v_mfma_f32_16x16x32_bf16 v[24:27], v[146:149], v[208:211], v[24:27]
	v_mul_f32_e32 v99, v103, v99
	v_cvt_pk_bf16_f32 v104, v104, v105
	v_cvt_pk_bf16_f32 v105, v106, v107
	v_cvt_pk_bf16_f32 v106, v96, v97
	v_cvt_pk_bf16_f32 v107, v98, v99
	global_store_dwordx4 v[232:233], v[104:107], off
	v_mfma_f32_16x16x32_bf16 v[16:19], v[158:161], v[208:211], v[16:19]
	v_lshl_add_u64 v[232:233], v[232:233], 0, s[98:99]
	v_mul_f32_e32 v88, v236, v88
	v_mul_f32_e32 v89, v236, v89
	v_mul_f32_e32 v90, v236, v90
	v_mul_f32_e32 v91, v236, v91
	v_mul_f32_e32 v92, v236, v92
	v_mfma_f32_16x16x32_bf16 v[8:11], v[146:149], v[216:219], v[8:11]
	v_mul_f32_e32 v93, v236, v93
	v_mul_f32_e32 v94, v236, v94
	v_mul_f32_e32 v95, v236, v95
	v_mul_f32_e32 v224, s100, v88
	v_mul_f32_e32 v225, s101, v89
	v_mul_f32_e32 v228, s100, v90
	v_mfma_f32_16x16x32_bf16 v[4:7], v[158:161], v[216:219], v[4:7]
	v_mul_f32_e32 v229, s101, v91
	v_exp_f32_e32 v224, v224
	v_exp_f32_e32 v225, v225
	v_exp_f32_e32 v228, v228
	v_exp_f32_e32 v229, v229
	v_add_f32_e32 v224, 1.0, v224
	v_mfma_f32_16x16x32_bf16 v[56:59], v[154:157], v[196:199], v[56:59]
	v_add_f32_e32 v225, 1.0, v225
	v_add_f32_e32 v228, 1.0, v228
	v_add_f32_e32 v229, 1.0, v229
	v_rcp_f32_e32 v224, v224
	v_rcp_f32_e32 v225, v225
	v_rcp_f32_e32 v228, v228
	v_mfma_f32_16x16x32_bf16 v[48:51], v[162:165], v[196:199], v[48:51]
	v_rcp_f32_e32 v229, v229
	v_nop
	v_mul_f32_e32 v88, v224, v88
	v_mul_f32_e32 v89, v225, v89
	v_mul_f32_e32 v90, v228, v90
	v_mul_f32_e32 v91, v229, v91
	v_mfma_f32_16x16x32_bf16 v[40:43], v[154:157], v[204:207], v[40:43]
	v_mul_f32_e32 v88, v92, v88
	v_mul_f32_e32 v89, v93, v89
	v_mul_f32_e32 v90, v94, v90
	v_mul_f32_e32 v91, v95, v91
	v_mul_f32_e32 v80, v236, v80
	v_mul_f32_e32 v81, v236, v81
	v_mfma_f32_16x16x32_bf16 v[32:35], v[162:165], v[204:207], v[32:35]
	v_mul_f32_e32 v82, v236, v82
	v_mul_f32_e32 v83, v236, v83
	v_mul_f32_e32 v84, v236, v84
	v_mul_f32_e32 v85, v236, v85
	v_mul_f32_e32 v86, v236, v86
	v_mul_f32_e32 v87, v236, v87
	v_mfma_f32_16x16x32_bf16 v[24:27], v[154:157], v[212:215], v[24:27]
	v_mul_f32_e32 v224, s100, v80
	v_mul_f32_e32 v225, s101, v81
	v_mul_f32_e32 v228, s100, v82
	v_mul_f32_e32 v229, s101, v83
	v_exp_f32_e32 v224, v224
	v_exp_f32_e32 v225, v225
	v_mfma_f32_16x16x32_bf16 v[16:19], v[162:165], v[212:215], v[16:19]
	v_exp_f32_e32 v228, v228
	v_exp_f32_e32 v229, v229
	v_add_f32_e32 v224, 1.0, v224
	v_add_f32_e32 v225, 1.0, v225
	v_add_f32_e32 v228, 1.0, v228
	v_add_f32_e32 v229, 1.0, v229
	v_mfma_f32_16x16x32_bf16 v[8:11], v[154:157], v[240:243], v[8:11]
	v_rcp_f32_e32 v224, v224
	v_rcp_f32_e32 v225, v225
	v_rcp_f32_e32 v228, v228
	v_rcp_f32_e32 v229, v229
	v_nop
	v_mul_f32_e32 v80, v224, v80
	v_mfma_f32_16x16x32_bf16 v[4:7], v[162:165], v[240:243], v[4:7]
	v_mul_f32_e32 v81, v225, v81
	v_mul_f32_e32 v82, v228, v82
	v_mul_f32_e32 v83, v229, v83
	v_mul_f32_e32 v80, v84, v80
	v_mul_f32_e32 v81, v85, v81
	v_mul_f32_e32 v82, v86, v82
	s_setprio 0
	s_setprio 1
	v_mfma_f32_16x16x32_bf16 v[60:63], v[176:179], v[192:195], v[60:63]
; __device__ __forceinline__ unsigned cvt_pk_bf16(float lo, float hi) { unsigned r; asm volatile("v_cvt_pk_bf16_f32 %0, %1, %2" : "=v"(r) : "v"(lo), "v"(hi)); return r; }
; __device__ __forceinline__ float siluf_(float x) { return x * sigmoidf_(x); }
; #define PG8_MMA(ai, bj, At, Bt) do { __builtin_amdgcn_s_setprio(1); _Pragma("unroll") for (int k = 0; k < 2; ++k) _Pragma("unroll") for (int m = 0; m < 4; ++m) _Pragma("unroll") for (int n = 0; n < 2; ++n) \
;         acc[ai][bj][m][n] = __builtin_amdgcn_mfma_f32_16x16x32_bf16(Bt[n][k], At[m][k], acc[ai][bj][m][n], 0, 0, 0); __builtin_amdgcn_s_setprio(0); } while (0)
; #define PG8_WAIT_V(n) asm volatile("s_waitcnt vmcnt(" #n ")" ::: "memory")
; #define PG8_BAR __builtin_amdgcn_s_barrier()
;     __device__ __forceinline__ void operator()(const f32x4 (&acc)[2][2][4][2], const Unit& u, int wr, int wc, int fr, int fq) const {
;     ...
;             for (int m = 0; m < 4; ++m) { const int row = row0 + ai * HALF + m * 16; bf16_t* rowp = O + (size_t)row * ldc + col0; const float rs = rsv[ai][m];
;                 f32x4 v0, v1;
; #pragma unroll
;                 for (int j = 0; j < 4; ++j) { v0[j] = siluf_(acc[ai][0][m][0][j] * rs) * (acc[ai][1][m][0][j] * rs); v1[j] = siluf_(acc[ai][0][m][1][j] * rs) * (acc[ai][1][m][1][j] * rs); }
;                 u32x4 w; w.x = cvt_pk_bf16(v0[0], v0[1]); w.y = cvt_pk_bf16(v0[2], v0[3]); w.z = cvt_pk_bf16(v1[0], v1[1]); w.w = cvt_pk_bf16(v1[2], v1[3]);
;                 *(u32x4*)rowp = w; }
; template <class Epi, bool ALIGN_EPI>
; __device__ __forceinline__ void gemm_phase(LAS unsigned char* lds, const Gemm g, const StaticOrder& S, const Epi& E, const int tid) {
;     ...
;             PG8_WAIT_V(8); PG8_WAIT_L(0); PG8_BAR; PG8_MMA(1, 0, At, B0); PG8_MMA(1, 1, At, B1); PG8_BAR; PG8_SCHED;
;         }
;         if constexpr (ALIGN_EPI) { if (wr == 0) PG8_BAR; }
;         { int t2 = tid; asm volatile("" : "+v"(t2)); const int l2 = t2 & 63, w2 = __builtin_amdgcn_readfirstlane(t2 >> 6); E(acc, cur, w2 >> 2, w2 & 3, l2 & 15, l2 >> 4); }
;         if (!has_next) break;
; #pragma unroll
;         for (int a = 0; a < 2; ++a)
; #pragma unroll
;             for (int b = 0; b < 2; ++b)
; #pragma unroll
;                 for (int m = 0; m < 4; ++m)
; #pragma unroll
;                     for (int n = 0; n < 2; ++n) acc[a][b][m][n] = (f32x4){0.f, 0.f, 0.f, 0.f};
;         cur = nxt; cA = nA; cB = nB; ++ui;
	v_mul_f32_e32 v83, v87, v83
	v_cvt_pk_bf16_f32 v88, v88, v89
	v_cvt_pk_bf16_f32 v89, v90, v91
	v_cvt_pk_bf16_f32 v90, v80, v81
	v_cvt_pk_bf16_f32 v91, v82, v83
	global_store_dwordx4 v[232:233], v[88:91], off
	v_mfma_f32_16x16x32_bf16 v[52:55], v[184:187], v[192:195], v[52:55]
	v_lshl_add_u64 v[232:233], v[232:233], 0, s[98:99]
	v_mul_f32_e32 v72, v237, v72
	v_mul_f32_e32 v73, v237, v73
	v_mul_f32_e32 v74, v237, v74
	v_mul_f32_e32 v75, v237, v75
	v_mul_f32_e32 v76, v237, v76
	v_mfma_f32_16x16x32_bf16 v[44:47], v[176:179], v[200:203], v[44:47]
	v_mul_f32_e32 v77, v237, v77
	v_mul_f32_e32 v78, v237, v78
	v_mul_f32_e32 v79, v237, v79
	v_mul_f32_e32 v224, s100, v72
	v_mul_f32_e32 v225, s101, v73
	v_mul_f32_e32 v228, s100, v74
	v_mfma_f32_16x16x32_bf16 v[36:39], v[184:187], v[200:203], v[36:39]
	v_mul_f32_e32 v229, s101, v75
	v_exp_f32_e32 v224, v224
	v_exp_f32_e32 v225, v225
	v_exp_f32_e32 v228, v228
	v_exp_f32_e32 v229, v229
	v_add_f32_e32 v224, 1.0, v224
	v_mfma_f32_16x16x32_bf16 v[28:31], v[176:179], v[208:211], v[28:31]
	v_add_f32_e32 v225, 1.0, v225
	v_add_f32_e32 v228, 1.0, v228
	v_add_f32_e32 v229, 1.0, v229
	v_rcp_f32_e32 v224, v224
	v_rcp_f32_e32 v225, v225
	v_rcp_f32_e32 v228, v228
	v_mfma_f32_16x16x32_bf16 v[20:23], v[184:187], v[208:211], v[20:23]
	v_rcp_f32_e32 v229, v229
	v_nop
	v_mul_f32_e32 v72, v224, v72
	v_mul_f32_e32 v73, v225, v73
	v_mul_f32_e32 v74, v228, v74
	v_mul_f32_e32 v75, v229, v75
	v_mfma_f32_16x16x32_bf16 v[12:15], v[176:179], v[216:219], v[12:15]
	v_mul_f32_e32 v72, v76, v72
	v_mul_f32_e32 v73, v77, v73
	v_mul_f32_e32 v74, v78, v74
	v_mul_f32_e32 v75, v79, v75
	v_mul_f32_e32 v64, v237, v64
	v_mul_f32_e32 v65, v237, v65
	v_mfma_f32_16x16x32_bf16 v[0:3], v[184:187], v[216:219], v[0:3]
	v_mul_f32_e32 v66, v237, v66
	v_mul_f32_e32 v67, v237, v67
	v_mul_f32_e32 v68, v237, v68
	v_mul_f32_e32 v69, v237, v69
	v_mul_f32_e32 v70, v237, v70
	v_mul_f32_e32 v71, v237, v71
	v_mfma_f32_16x16x32_bf16 v[60:63], v[180:183], v[196:199], v[60:63]
	v_mul_f32_e32 v224, s100, v64
	v_mul_f32_e32 v225, s101, v65
	v_mul_f32_e32 v228, s100, v66
	v_mul_f32_e32 v229, s101, v67
	v_exp_f32_e32 v224, v224
	v_exp_f32_e32 v225, v225
	v_mfma_f32_16x16x32_bf16 v[52:55], v[188:191], v[196:199], v[52:55]
	v_exp_f32_e32 v228, v228
	v_exp_f32_e32 v229, v229
	v_add_f32_e32 v224, 1.0, v224
	v_add_f32_e32 v225, 1.0, v225
	v_add_f32_e32 v228, 1.0, v228
	v_add_f32_e32 v229, 1.0, v229
	v_mfma_f32_16x16x32_bf16 v[44:47], v[180:183], v[204:207], v[44:47]
	v_rcp_f32_e32 v224, v224
	v_rcp_f32_e32 v225, v225
	v_rcp_f32_e32 v228, v228
	v_rcp_f32_e32 v229, v229
	v_nop
	v_mul_f32_e32 v64, v224, v64
	v_mfma_f32_16x16x32_bf16 v[36:39], v[188:191], v[204:207], v[36:39]
	v_mul_f32_e32 v65, v225, v65
	v_mul_f32_e32 v66, v228, v66
	v_mul_f32_e32 v67, v229, v67
	v_mul_f32_e32 v64, v68, v64
	v_mul_f32_e32 v65, v69, v65
	v_mul_f32_e32 v66, v70, v66
	v_mfma_f32_16x16x32_bf16 v[28:31], v[180:183], v[212:215], v[28:31]
	v_mul_f32_e32 v67, v71, v67
	v_cvt_pk_bf16_f32 v72, v72, v73
	v_cvt_pk_bf16_f32 v73, v74, v75
	v_cvt_pk_bf16_f32 v74, v64, v65
	v_cvt_pk_bf16_f32 v75, v66, v67
	global_store_dwordx4 v[232:233], v[72:75], off
	v_mfma_f32_16x16x32_bf16 v[20:23], v[188:191], v[212:215], v[20:23]
	v_lshl_add_u64 v[232:233], v[232:233], 0, s[98:99]
	v_lshl_add_u64 v[232:233], v[232:233], 0, s[98:99]
	v_lshl_add_u64 v[232:233], v[232:233], 0, s[98:99]
	v_lshl_add_u64 v[232:233], v[232:233], 0, s[98:99]
	v_lshl_add_u64 v[232:233], v[232:233], 0, s[98:99]
	v_mfma_f32_16x16x32_bf16 v[12:15], v[180:183], v[240:243], v[12:15]
	v_mfma_f32_16x16x32_bf16 v[0:3], v[188:191], v[240:243], v[0:3]
	s_setprio 0
	s_barrier
	v_lshl_add_u64 v[142:143], v[142:143], 0, s[80:81]
	v_lshl_add_u64 v[144:145], v[144:145], 0, s[80:81]
	s_and_b64 vcc, exec, s[8:9]
	s_cbranch_vccnz .Lgu_notdefer
	s_cmp_lg_u32 s62, s64
	s_cbranch_scc1 .Lgu_notdefer
	s_mov_b32 s101, 1
	s_mov_b32 s63, s61
	s_mov_b32 s64, s62
	v_mov_b64_e32 v[144:145], v[140:141]
	v_mov_b64_e32 v[142:143], v[138:139]
	s_branch .LBB0_300
